# same setprio-pair removal in all nine GEMM K-loops
# baseline (speedup 1.0000x reference)
.LBB0_143:
	ds_read_b128 v[168:171], v163
	ds_read_b128 v[172:175], v163 offset:1024
	ds_read_b128 v[176:179], v163 offset:2048
	ds_read_b128 v[180:183], v163 offset:3072
	ds_read_b128 v[184:187], v164
	ds_read_b128 v[188:191], v164 offset:1024
	ds_read_b128 v[192:195], v164 offset:2048
	ds_read_b128 v[196:199], v164 offset:3072
	s_add_u32 s26, s24, 0xfff80080
	s_addc_u32 s27, s25, -1
	s_cmp_eq_u32 s62, 28
	s_cselect_b32 s31, s15, s27
	s_cselect_b32 s30, s23, s26
	s_cselect_b32 s27, s13, s61
	s_cselect_b32 s26, s59, s60
	v_lshl_add_u64 v[154:155], s[24:25], 0, v[144:145]
	s_add_i32 m0, s43, 0xc000
	ds_read_b128 v[200:203], v165
	ds_read_b128 v[204:207], v165 offset:1024
	ds_read_b128 v[208:211], v165 offset:2048
	ds_read_b128 v[212:215], v165 offset:3072
	ds_read_b128 v[216:219], v165 offset:4096
	ds_read_b128 v[220:223], v165 offset:5120
	ds_read_b128 v[224:227], v165 offset:6144
	ds_read_b128 v[228:231], v165 offset:7168
	global_load_lds_dwordx4 v[154:155], off
	v_lshl_add_u64 v[154:155], s[24:25], 0, v[142:143]
	s_add_i32 m0, s43, 0xe000
	s_nop 0
	global_load_lds_dwordx4 v[154:155], off
	s_waitcnt vmcnt(8)
	s_waitcnt lgkmcnt(0)
	s_barrier
	s_setprio 1
	s_waitcnt lgkmcnt(0)
	v_mfma_f32_16x16x32_bf16 v[126:129], v[168:171], v[200:203], v[126:129]
	v_mfma_f32_16x16x32_bf16 v[122:125], v[176:179], v[200:203], v[122:125]
	v_mfma_f32_16x16x32_bf16 v[114:117], v[168:171], v[208:211], v[114:117]
	v_mfma_f32_16x16x32_bf16 v[106:109], v[176:179], v[208:211], v[106:109]
	v_mfma_f32_16x16x32_bf16 v[98:101], v[168:171], v[216:219], v[98:101]
	v_mfma_f32_16x16x32_bf16 v[90:93], v[176:179], v[216:219], v[90:93]
	v_mfma_f32_16x16x32_bf16 v[82:85], v[168:171], v[224:227], v[82:85]
	v_mfma_f32_16x16x32_bf16 v[74:77], v[176:179], v[224:227], v[74:77]
	v_mfma_f32_16x16x32_bf16 v[126:129], v[172:175], v[204:207], v[126:129]
	v_mfma_f32_16x16x32_bf16 v[122:125], v[180:183], v[204:207], v[122:125]
	v_mfma_f32_16x16x32_bf16 v[114:117], v[172:175], v[212:215], v[114:117]
	v_mfma_f32_16x16x32_bf16 v[106:109], v[180:183], v[212:215], v[106:109]
	v_mfma_f32_16x16x32_bf16 v[98:101], v[172:175], v[220:223], v[98:101]
	v_mfma_f32_16x16x32_bf16 v[90:93], v[180:183], v[220:223], v[90:93]
	v_mfma_f32_16x16x32_bf16 v[82:85], v[172:175], v[228:231], v[82:85]
	v_mfma_f32_16x16x32_bf16 v[74:77], v[180:183], v[228:231], v[74:77]
	v_mfma_f32_16x16x32_bf16 v[118:121], v[184:187], v[200:203], v[118:121]
	v_mfma_f32_16x16x32_bf16 v[110:113], v[192:195], v[200:203], v[110:113]
	v_mfma_f32_16x16x32_bf16 v[102:105], v[184:187], v[208:211], v[102:105]
	v_mfma_f32_16x16x32_bf16 v[94:97], v[192:195], v[208:211], v[94:97]
	v_mfma_f32_16x16x32_bf16 v[86:89], v[184:187], v[216:219], v[86:89]
	v_mfma_f32_16x16x32_bf16 v[78:81], v[192:195], v[216:219], v[78:81]
	v_mfma_f32_16x16x32_bf16 v[70:73], v[184:187], v[224:227], v[70:73]
	v_mfma_f32_16x16x32_bf16 v[66:69], v[192:195], v[224:227], v[66:69]
	v_mfma_f32_16x16x32_bf16 v[118:121], v[188:191], v[204:207], v[118:121]
	v_mfma_f32_16x16x32_bf16 v[110:113], v[196:199], v[204:207], v[110:113]
	v_mfma_f32_16x16x32_bf16 v[102:105], v[188:191], v[212:215], v[102:105]
	v_mfma_f32_16x16x32_bf16 v[94:97], v[196:199], v[212:215], v[94:97]
	v_mfma_f32_16x16x32_bf16 v[86:89], v[188:191], v[220:223], v[86:89]
	v_mfma_f32_16x16x32_bf16 v[78:81], v[196:199], v[220:223], v[78:81]
	v_mfma_f32_16x16x32_bf16 v[70:73], v[188:191], v[228:231], v[70:73]
	v_mfma_f32_16x16x32_bf16 v[66:69], v[196:199], v[228:231], v[66:69]
	s_setprio 0
	s_barrier
	s_add_i32 s63, s55, s42
	v_lshl_add_u64 v[154:155], s[26:27], 0, v[132:133]
	s_mov_b32 m0, s63
	ds_read_b128 v[200:203], v165 offset:16384
	ds_read_b128 v[204:207], v165 offset:17408
	ds_read_b128 v[208:211], v165 offset:18432
	ds_read_b128 v[212:215], v165 offset:19456
	ds_read_b128 v[216:219], v165 offset:20480
	ds_read_b128 v[220:223], v165 offset:21504
	ds_read_b128 v[224:227], v165 offset:22528
	ds_read_b128 v[228:231], v165 offset:23552
	global_load_lds_dwordx4 v[154:155], off
	s_add_i32 m0, s63, 0x2000
	s_add_u32 s64, s26, 0x80000
	v_lshl_add_u64 v[232:233], s[26:27], 0, v[136:137]
	s_addc_u32 s65, s27, 0
	s_add_i32 s63, s56, s42
	global_load_lds_dwordx4 v[232:233], off
	v_lshl_add_u64 v[234:235], s[64:65], 0, v[132:133]
	s_mov_b32 m0, s63
	v_lshl_add_u64 v[236:237], s[30:31], 0, v[134:135]
	global_load_lds_dwordx4 v[234:235], off
	v_lshl_add_u64 v[234:235], s[64:65], 0, v[136:137]
	s_add_i32 m0, s63, 0x2000
	s_nop 0
	global_load_lds_dwordx4 v[234:235], off
	v_lshl_add_u64 v[234:235], s[30:31], 0, v[130:131]
	s_mov_b32 m0, s43
	s_nop 0
	global_load_lds_dwordx4 v[234:235], off
	s_mov_b32 m0, s44
	s_nop 0
	global_load_lds_dwordx4 v[236:237], off
	s_waitcnt vmcnt(8)
	s_waitcnt lgkmcnt(0)
	s_barrier
	s_setprio 1
	s_waitcnt lgkmcnt(0)
	v_mfma_f32_16x16x32_bf16 v[62:65], v[168:171], v[200:203], v[62:65]
	v_mfma_f32_16x16x32_bf16 v[58:61], v[176:179], v[200:203], v[58:61]
	v_mfma_f32_16x16x32_bf16 v[50:53], v[168:171], v[208:211], v[50:53]
	v_mfma_f32_16x16x32_bf16 v[42:45], v[176:179], v[208:211], v[42:45]
	v_mfma_f32_16x16x32_bf16 v[34:37], v[168:171], v[216:219], v[34:37]
	v_mfma_f32_16x16x32_bf16 v[26:29], v[176:179], v[216:219], v[26:29]
	v_mfma_f32_16x16x32_bf16 v[18:21], v[168:171], v[224:227], v[18:21]
	v_mfma_f32_16x16x32_bf16 v[10:13], v[176:179], v[224:227], v[10:13]
	v_mfma_f32_16x16x32_bf16 v[62:65], v[172:175], v[204:207], v[62:65]
	v_mfma_f32_16x16x32_bf16 v[58:61], v[180:183], v[204:207], v[58:61]
	v_mfma_f32_16x16x32_bf16 v[50:53], v[172:175], v[212:215], v[50:53]
	v_mfma_f32_16x16x32_bf16 v[42:45], v[180:183], v[212:215], v[42:45]
	v_mfma_f32_16x16x32_bf16 v[34:37], v[172:175], v[220:223], v[34:37]
	v_mfma_f32_16x16x32_bf16 v[26:29], v[180:183], v[220:223], v[26:29]
	v_mfma_f32_16x16x32_bf16 v[18:21], v[172:175], v[228:231], v[18:21]
	v_mfma_f32_16x16x32_bf16 v[10:13], v[180:183], v[228:231], v[10:13]
	v_mfma_f32_16x16x32_bf16 v[54:57], v[184:187], v[200:203], v[54:57]
	v_mfma_f32_16x16x32_bf16 v[46:49], v[192:195], v[200:203], v[46:49]
	v_mfma_f32_16x16x32_bf16 v[38:41], v[184:187], v[208:211], v[38:41]
	v_mfma_f32_16x16x32_bf16 v[30:33], v[192:195], v[208:211], v[30:33]
	v_mfma_f32_16x16x32_bf16 v[22:25], v[184:187], v[216:219], v[22:25]
	v_mfma_f32_16x16x32_bf16 v[14:17], v[192:195], v[216:219], v[14:17]
	v_mfma_f32_16x16x32_bf16 v[6:9], v[184:187], v[224:227], v[6:9]
	v_mfma_f32_16x16x32_bf16 v[2:5], v[192:195], v[224:227], v[2:5]
	v_mfma_f32_16x16x32_bf16 v[54:57], v[188:191], v[204:207], v[54:57]
	v_mfma_f32_16x16x32_bf16 v[46:49], v[196:199], v[204:207], v[46:49]
	v_mfma_f32_16x16x32_bf16 v[38:41], v[188:191], v[212:215], v[38:41]
	v_mfma_f32_16x16x32_bf16 v[30:33], v[196:199], v[212:215], v[30:33]
	v_mfma_f32_16x16x32_bf16 v[22:25], v[188:191], v[220:223], v[22:25]
	v_mfma_f32_16x16x32_bf16 v[14:17], v[196:199], v[220:223], v[14:17]
	v_mfma_f32_16x16x32_bf16 v[6:9], v[188:191], v[228:231], v[6:9]
	v_mfma_f32_16x16x32_bf16 v[2:5], v[196:199], v[228:231], v[2:5]
	s_setprio 0
	s_barrier
	s_add_i32 s63, 0, 0x18000
	v_add_u32_e32 v138, s63, v159
	s_add_i32 s64, 0, 0x1c000
	ds_read_b128 v[168:171], v138
	ds_read_b128 v[172:175], v138 offset:1024
	ds_read_b128 v[176:179], v138 offset:2048
	ds_read_b128 v[180:183], v138 offset:3072
	v_add_u32_e32 v138, s64, v159
	ds_read_b128 v[184:187], v138
	ds_read_b128 v[188:191], v138 offset:1024
	ds_read_b128 v[192:195], v138 offset:2048
	ds_read_b128 v[196:199], v138 offset:3072
	s_add_u32 s30, s30, 0x80000
	s_addc_u32 s31, s31, 0
	s_mov_b32 m0, s45
	v_lshl_add_u64 v[238:239], s[30:31], 0, v[130:131]
	ds_read_b128 v[200:203], v165 offset:32768
	ds_read_b128 v[204:207], v165 offset:33792
	ds_read_b128 v[208:211], v165 offset:34816
	ds_read_b128 v[212:215], v165 offset:35840
	ds_read_b128 v[216:219], v165 offset:36864
	ds_read_b128 v[220:223], v165 offset:37888
	ds_read_b128 v[224:227], v165 offset:38912
	ds_read_b128 v[228:231], v165 offset:39936
	global_load_lds_dwordx4 v[238:239], off
	v_lshl_add_u64 v[238:239], s[30:31], 0, v[134:135]
	s_mov_b32 m0, s46
	s_nop 0
	global_load_lds_dwordx4 v[238:239], off
	s_waitcnt vmcnt(8)
	s_waitcnt lgkmcnt(0)
	s_barrier
	s_setprio 1
	s_waitcnt lgkmcnt(0)
	v_mfma_f32_16x16x32_bf16 v[126:129], v[168:171], v[200:203], v[126:129]
	v_mfma_f32_16x16x32_bf16 v[122:125], v[176:179], v[200:203], v[122:125]
	v_mfma_f32_16x16x32_bf16 v[114:117], v[168:171], v[208:211], v[114:117]
	v_mfma_f32_16x16x32_bf16 v[106:109], v[176:179], v[208:211], v[106:109]
	v_mfma_f32_16x16x32_bf16 v[98:101], v[168:171], v[216:219], v[98:101]
	v_mfma_f32_16x16x32_bf16 v[90:93], v[176:179], v[216:219], v[90:93]
	v_mfma_f32_16x16x32_bf16 v[82:85], v[168:171], v[224:227], v[82:85]
	v_mfma_f32_16x16x32_bf16 v[74:77], v[176:179], v[224:227], v[74:77]
	v_mfma_f32_16x16x32_bf16 v[126:129], v[172:175], v[204:207], v[126:129]
	v_mfma_f32_16x16x32_bf16 v[122:125], v[180:183], v[204:207], v[122:125]
	v_mfma_f32_16x16x32_bf16 v[114:117], v[172:175], v[212:215], v[114:117]
	v_mfma_f32_16x16x32_bf16 v[106:109], v[180:183], v[212:215], v[106:109]
	v_mfma_f32_16x16x32_bf16 v[98:101], v[172:175], v[220:223], v[98:101]
	v_mfma_f32_16x16x32_bf16 v[90:93], v[180:183], v[220:223], v[90:93]
	v_mfma_f32_16x16x32_bf16 v[82:85], v[172:175], v[228:231], v[82:85]
	v_mfma_f32_16x16x32_bf16 v[74:77], v[180:183], v[228:231], v[74:77]
	v_mfma_f32_16x16x32_bf16 v[118:121], v[184:187], v[200:203], v[118:121]
	v_mfma_f32_16x16x32_bf16 v[110:113], v[192:195], v[200:203], v[110:113]
	v_mfma_f32_16x16x32_bf16 v[102:105], v[184:187], v[208:211], v[102:105]
	v_mfma_f32_16x16x32_bf16 v[94:97], v[192:195], v[208:211], v[94:97]
	v_mfma_f32_16x16x32_bf16 v[86:89], v[184:187], v[216:219], v[86:89]
	v_mfma_f32_16x16x32_bf16 v[78:81], v[192:195], v[216:219], v[78:81]
	v_mfma_f32_16x16x32_bf16 v[70:73], v[184:187], v[224:227], v[70:73]
	v_mfma_f32_16x16x32_bf16 v[66:69], v[192:195], v[224:227], v[66:69]
	v_mfma_f32_16x16x32_bf16 v[118:121], v[188:191], v[204:207], v[118:121]
	v_mfma_f32_16x16x32_bf16 v[110:113], v[196:199], v[204:207], v[110:113]
	v_mfma_f32_16x16x32_bf16 v[102:105], v[188:191], v[212:215], v[102:105]
	v_mfma_f32_16x16x32_bf16 v[94:97], v[196:199], v[212:215], v[94:97]
	v_mfma_f32_16x16x32_bf16 v[86:89], v[188:191], v[220:223], v[86:89]
	v_mfma_f32_16x16x32_bf16 v[78:81], v[196:199], v[220:223], v[78:81]
	v_mfma_f32_16x16x32_bf16 v[70:73], v[188:191], v[228:231], v[70:73]
	v_mfma_f32_16x16x32_bf16 v[66:69], v[196:199], v[228:231], v[66:69]
	s_setprio 0
	s_barrier
	s_add_i32 s30, s63, s42
	v_lshl_add_u64 v[154:155], v[154:155], 0, s[8:9]
	s_mov_b32 m0, s30
	ds_read_b128 v[200:203], v165 offset:49152
	ds_read_b128 v[204:207], v165 offset:50176
	ds_read_b128 v[208:211], v165 offset:51200
	ds_read_b128 v[212:215], v165 offset:52224
	ds_read_b128 v[216:219], v165 offset:53248
	ds_read_b128 v[220:223], v165 offset:54272
	ds_read_b128 v[224:227], v165 offset:55296
	ds_read_b128 v[228:231], v165 offset:56320
	global_load_lds_dwordx4 v[154:155], off
	s_add_i32 m0, s30, 0x2000
	s_add_u32 s26, s26, 0x80080
	v_lshl_add_u64 v[154:155], v[232:233], 0, s[8:9]
	s_addc_u32 s27, s27, 0
	s_add_i32 s30, s64, s42
	global_load_lds_dwordx4 v[154:155], off
	v_lshl_add_u64 v[154:155], s[26:27], 0, v[132:133]
	s_mov_b32 m0, s30
	s_nop 0
	global_load_lds_dwordx4 v[154:155], off
	v_lshl_add_u64 v[154:155], s[26:27], 0, v[136:137]
	s_add_i32 m0, s30, 0x2000
	s_nop 0
	global_load_lds_dwordx4 v[154:155], off
	v_lshl_add_u64 v[154:155], v[234:235], 0, s[8:9]
	s_mov_b32 m0, s51
	s_nop 0
	global_load_lds_dwordx4 v[154:155], off
	v_lshl_add_u64 v[154:155], v[236:237], 0, s[8:9]
	s_mov_b32 m0, s53
	s_nop 0
	global_load_lds_dwordx4 v[154:155], off
	s_waitcnt vmcnt(8)
	s_waitcnt lgkmcnt(0)
	s_barrier
	s_setprio 1
	s_waitcnt lgkmcnt(0)
	v_mfma_f32_16x16x32_bf16 v[62:65], v[168:171], v[200:203], v[62:65]
	v_mfma_f32_16x16x32_bf16 v[58:61], v[176:179], v[200:203], v[58:61]
	v_mfma_f32_16x16x32_bf16 v[50:53], v[168:171], v[208:211], v[50:53]
	v_mfma_f32_16x16x32_bf16 v[42:45], v[176:179], v[208:211], v[42:45]
	v_mfma_f32_16x16x32_bf16 v[34:37], v[168:171], v[216:219], v[34:37]
	v_mfma_f32_16x16x32_bf16 v[26:29], v[176:179], v[216:219], v[26:29]
	v_mfma_f32_16x16x32_bf16 v[18:21], v[168:171], v[224:227], v[18:21]
	v_mfma_f32_16x16x32_bf16 v[10:13], v[176:179], v[224:227], v[10:13]
	v_mfma_f32_16x16x32_bf16 v[62:65], v[172:175], v[204:207], v[62:65]
	v_mfma_f32_16x16x32_bf16 v[58:61], v[180:183], v[204:207], v[58:61]
	v_mfma_f32_16x16x32_bf16 v[50:53], v[172:175], v[212:215], v[50:53]
	v_mfma_f32_16x16x32_bf16 v[42:45], v[180:183], v[212:215], v[42:45]
	v_mfma_f32_16x16x32_bf16 v[34:37], v[172:175], v[220:223], v[34:37]
	v_mfma_f32_16x16x32_bf16 v[26:29], v[180:183], v[220:223], v[26:29]
	v_mfma_f32_16x16x32_bf16 v[18:21], v[172:175], v[228:231], v[18:21]
	v_mfma_f32_16x16x32_bf16 v[10:13], v[180:183], v[228:231], v[10:13]
	v_mfma_f32_16x16x32_bf16 v[54:57], v[184:187], v[200:203], v[54:57]
	v_mfma_f32_16x16x32_bf16 v[46:49], v[192:195], v[200:203], v[46:49]
	v_mfma_f32_16x16x32_bf16 v[38:41], v[184:187], v[208:211], v[38:41]
	v_mfma_f32_16x16x32_bf16 v[30:33], v[192:195], v[208:211], v[30:33]
	v_mfma_f32_16x16x32_bf16 v[22:25], v[184:187], v[216:219], v[22:25]
	v_mfma_f32_16x16x32_bf16 v[14:17], v[192:195], v[216:219], v[14:17]
	v_mfma_f32_16x16x32_bf16 v[6:9], v[184:187], v[224:227], v[6:9]
	v_mfma_f32_16x16x32_bf16 v[2:5], v[192:195], v[224:227], v[2:5]
	v_mfma_f32_16x16x32_bf16 v[54:57], v[188:191], v[204:207], v[54:57]
	v_mfma_f32_16x16x32_bf16 v[46:49], v[196:199], v[204:207], v[46:49]
	v_mfma_f32_16x16x32_bf16 v[38:41], v[188:191], v[212:215], v[38:41]
	v_mfma_f32_16x16x32_bf16 v[30:33], v[196:199], v[212:215], v[30:33]
	v_mfma_f32_16x16x32_bf16 v[22:25], v[188:191], v[220:223], v[22:25]
	v_mfma_f32_16x16x32_bf16 v[14:17], v[196:199], v[220:223], v[14:17]
	v_mfma_f32_16x16x32_bf16 v[6:9], v[188:191], v[228:231], v[6:9]
	v_mfma_f32_16x16x32_bf16 v[2:5], v[196:199], v[228:231], v[2:5]
	s_setprio 0
	s_barrier
	s_add_i32 s62, s62, 2
	s_add_u32 s60, s60, 0x100
	s_addc_u32 s61, s61, 0
	s_add_u32 s24, s24, 0x100
	s_addc_u32 s25, s25, 0
	s_cmp_gt_u32 s62, 29
	s_cbranch_scc0 .LBB0_143
	s_and_b64 vcc, exec, s[10:11]
	s_cbranch_vccz .LBB0_146
	s_barrier

.LBB0_268:
	ds_read_b128 v[150:153], v139
	ds_read_b128 v[154:157], v139 offset:1024
	ds_read_b128 v[158:161], v139 offset:2048
	ds_read_b128 v[162:165], v139 offset:3072
	ds_read_b128 v[166:169], v146
	ds_read_b128 v[170:173], v146 offset:1024
	ds_read_b128 v[174:177], v146 offset:2048
	ds_read_b128 v[178:181], v146 offset:3072
	s_add_u32 s18, s14, s16
	s_addc_u32 s19, s15, s17
	s_add_u32 s18, s18, 0x28300100
	s_addc_u32 s19, s19, 0
	s_add_u32 s55, s41, s16
	s_addc_u32 s56, s42, s17
	s_cmpk_eq_i32 s16, 0x300
	s_cselect_b32 s23, s11, s19
	s_cselect_b32 s22, s10, s18
	s_cselect_b32 s19, s9, s56
	s_cselect_b32 s18, s8, s55
	s_mov_b32 m0, s44
	v_lshl_add_u64 v[214:215], v[142:143], 0, s[16:17]
	ds_read_b128 v[182:185], v147
	ds_read_b128 v[186:189], v147 offset:1024
	ds_read_b128 v[190:193], v147 offset:2048
	ds_read_b128 v[194:197], v147 offset:3072
	ds_read_b128 v[198:201], v147 offset:4096
	ds_read_b128 v[202:205], v147 offset:5120
	ds_read_b128 v[206:209], v147 offset:6144
	ds_read_b128 v[210:213], v147 offset:7168
	global_load_lds_dwordx4 v[214:215], off
	v_lshl_add_u64 v[214:215], v[140:141], 0, s[16:17]
	s_mov_b32 m0, s45
	s_nop 0
	global_load_lds_dwordx4 v[214:215], off
	s_waitcnt vmcnt(8)
	s_waitcnt lgkmcnt(0)
	s_barrier
	s_setprio 1
	s_waitcnt lgkmcnt(0)
	v_mfma_f32_16x16x32_bf16 v[126:129], v[150:153], v[182:185], v[126:129]
	v_mfma_f32_16x16x32_bf16 v[122:125], v[158:161], v[182:185], v[122:125]
	v_mfma_f32_16x16x32_bf16 v[118:121], v[150:153], v[190:193], v[118:121]
	v_mfma_f32_16x16x32_bf16 v[110:113], v[158:161], v[190:193], v[110:113]
	v_mfma_f32_16x16x32_bf16 v[102:105], v[150:153], v[198:201], v[102:105]
	v_mfma_f32_16x16x32_bf16 v[94:97], v[158:161], v[198:201], v[94:97]
	v_mfma_f32_16x16x32_bf16 v[86:89], v[150:153], v[206:209], v[86:89]
	v_mfma_f32_16x16x32_bf16 v[78:81], v[158:161], v[206:209], v[78:81]
	v_mfma_f32_16x16x32_bf16 v[126:129], v[154:157], v[186:189], v[126:129]
	v_mfma_f32_16x16x32_bf16 v[122:125], v[162:165], v[186:189], v[122:125]
	v_mfma_f32_16x16x32_bf16 v[118:121], v[154:157], v[194:197], v[118:121]
	v_mfma_f32_16x16x32_bf16 v[110:113], v[162:165], v[194:197], v[110:113]
	v_mfma_f32_16x16x32_bf16 v[102:105], v[154:157], v[202:205], v[102:105]
	v_mfma_f32_16x16x32_bf16 v[94:97], v[162:165], v[202:205], v[94:97]
	v_mfma_f32_16x16x32_bf16 v[86:89], v[154:157], v[210:213], v[86:89]
	v_mfma_f32_16x16x32_bf16 v[78:81], v[162:165], v[210:213], v[78:81]
	v_mfma_f32_16x16x32_bf16 v[114:117], v[166:169], v[182:185], v[114:117]
	v_mfma_f32_16x16x32_bf16 v[106:109], v[174:177], v[182:185], v[106:109]
	v_mfma_f32_16x16x32_bf16 v[98:101], v[166:169], v[190:193], v[98:101]
	v_mfma_f32_16x16x32_bf16 v[90:93], v[174:177], v[190:193], v[90:93]
	v_mfma_f32_16x16x32_bf16 v[82:85], v[166:169], v[198:201], v[82:85]
	v_mfma_f32_16x16x32_bf16 v[74:77], v[174:177], v[198:201], v[74:77]
	v_mfma_f32_16x16x32_bf16 v[70:73], v[166:169], v[206:209], v[70:73]
	v_mfma_f32_16x16x32_bf16 v[66:69], v[174:177], v[206:209], v[66:69]
	v_mfma_f32_16x16x32_bf16 v[114:117], v[170:173], v[186:189], v[114:117]
	v_mfma_f32_16x16x32_bf16 v[106:109], v[178:181], v[186:189], v[106:109]
	v_mfma_f32_16x16x32_bf16 v[98:101], v[170:173], v[194:197], v[98:101]
	v_mfma_f32_16x16x32_bf16 v[90:93], v[178:181], v[194:197], v[90:93]
	v_mfma_f32_16x16x32_bf16 v[82:85], v[170:173], v[202:205], v[82:85]
	v_mfma_f32_16x16x32_bf16 v[74:77], v[178:181], v[202:205], v[74:77]
	v_mfma_f32_16x16x32_bf16 v[70:73], v[170:173], v[210:213], v[70:73]
	v_mfma_f32_16x16x32_bf16 v[66:69], v[178:181], v[210:213], v[66:69]
	s_setprio 0
	s_barrier
	s_mov_b32 m0, s46
	v_lshl_add_u64 v[214:215], s[18:19], 0, v[132:133]
	s_add_u32 s56, s18, 0x20000
	ds_read_b128 v[182:185], v147 offset:16384
	ds_read_b128 v[186:189], v147 offset:17408
	ds_read_b128 v[190:193], v147 offset:18432
	ds_read_b128 v[194:197], v147 offset:19456
	ds_read_b128 v[198:201], v147 offset:20480
	ds_read_b128 v[202:205], v147 offset:21504
	ds_read_b128 v[206:209], v147 offset:22528
	ds_read_b128 v[210:213], v147 offset:23552
	global_load_lds_dwordx4 v[214:215], off
	v_lshl_add_u64 v[216:217], s[18:19], 0, v[136:137]
	s_mov_b32 m0, s47
	s_addc_u32 s57, s19, 0
	global_load_lds_dwordx4 v[216:217], off
	v_lshl_add_u64 v[218:219], s[56:57], 0, v[132:133]
	s_mov_b32 m0, s48
	v_lshl_add_u64 v[220:221], s[22:23], 0, v[134:135]
	global_load_lds_dwordx4 v[218:219], off
	v_lshl_add_u64 v[218:219], s[56:57], 0, v[136:137]
	s_mov_b32 m0, s49
	s_nop 0
	global_load_lds_dwordx4 v[218:219], off
	v_lshl_add_u64 v[218:219], s[22:23], 0, v[130:131]
	s_mov_b32 m0, s7
	s_nop 0
	global_load_lds_dwordx4 v[218:219], off
	s_mov_b32 m0, s36
	s_nop 0
	global_load_lds_dwordx4 v[220:221], off
	s_waitcnt vmcnt(8)
	s_waitcnt lgkmcnt(0)
	s_barrier
	s_setprio 1
	s_waitcnt lgkmcnt(0)
	v_mfma_f32_16x16x32_bf16 v[62:65], v[150:153], v[182:185], v[62:65]
	v_mfma_f32_16x16x32_bf16 v[58:61], v[158:161], v[182:185], v[58:61]
	v_mfma_f32_16x16x32_bf16 v[54:57], v[150:153], v[190:193], v[54:57]
	v_mfma_f32_16x16x32_bf16 v[46:49], v[158:161], v[190:193], v[46:49]
	v_mfma_f32_16x16x32_bf16 v[38:41], v[150:153], v[198:201], v[38:41]
	v_mfma_f32_16x16x32_bf16 v[30:33], v[158:161], v[198:201], v[30:33]
	v_mfma_f32_16x16x32_bf16 v[22:25], v[150:153], v[206:209], v[22:25]
	v_mfma_f32_16x16x32_bf16 v[14:17], v[158:161], v[206:209], v[14:17]
	v_mfma_f32_16x16x32_bf16 v[62:65], v[154:157], v[186:189], v[62:65]
	v_mfma_f32_16x16x32_bf16 v[58:61], v[162:165], v[186:189], v[58:61]
	v_mfma_f32_16x16x32_bf16 v[54:57], v[154:157], v[194:197], v[54:57]
	v_mfma_f32_16x16x32_bf16 v[46:49], v[162:165], v[194:197], v[46:49]
	v_mfma_f32_16x16x32_bf16 v[38:41], v[154:157], v[202:205], v[38:41]
	v_mfma_f32_16x16x32_bf16 v[30:33], v[162:165], v[202:205], v[30:33]
	v_mfma_f32_16x16x32_bf16 v[22:25], v[154:157], v[210:213], v[22:25]
	v_mfma_f32_16x16x32_bf16 v[14:17], v[162:165], v[210:213], v[14:17]
	v_mfma_f32_16x16x32_bf16 v[50:53], v[166:169], v[182:185], v[50:53]
	v_mfma_f32_16x16x32_bf16 v[42:45], v[174:177], v[182:185], v[42:45]
	v_mfma_f32_16x16x32_bf16 v[34:37], v[166:169], v[190:193], v[34:37]
	v_mfma_f32_16x16x32_bf16 v[26:29], v[174:177], v[190:193], v[26:29]
	v_mfma_f32_16x16x32_bf16 v[18:21], v[166:169], v[198:201], v[18:21]
	v_mfma_f32_16x16x32_bf16 v[10:13], v[174:177], v[198:201], v[10:13]
	v_mfma_f32_16x16x32_bf16 v[6:9], v[166:169], v[206:209], v[6:9]
	v_mfma_f32_16x16x32_bf16 v[2:5], v[174:177], v[206:209], v[2:5]
	v_mfma_f32_16x16x32_bf16 v[50:53], v[170:173], v[186:189], v[50:53]
	v_mfma_f32_16x16x32_bf16 v[42:45], v[178:181], v[186:189], v[42:45]
	v_mfma_f32_16x16x32_bf16 v[34:37], v[170:173], v[194:197], v[34:37]
	v_mfma_f32_16x16x32_bf16 v[26:29], v[178:181], v[194:197], v[26:29]
	v_mfma_f32_16x16x32_bf16 v[18:21], v[170:173], v[202:205], v[18:21]
	v_mfma_f32_16x16x32_bf16 v[10:13], v[178:181], v[202:205], v[10:13]
	v_mfma_f32_16x16x32_bf16 v[6:9], v[170:173], v[210:213], v[6:9]
	v_mfma_f32_16x16x32_bf16 v[2:5], v[178:181], v[210:213], v[2:5]
	s_setprio 0
	s_barrier
	ds_read_b128 v[150:153], v148
	ds_read_b128 v[154:157], v148 offset:1024
	ds_read_b128 v[158:161], v148 offset:2048
	ds_read_b128 v[162:165], v148 offset:3072
	ds_read_b128 v[166:169], v149
	ds_read_b128 v[170:173], v149 offset:1024
	ds_read_b128 v[174:177], v149 offset:2048
	ds_read_b128 v[178:181], v149 offset:3072
	s_add_u32 s22, s22, 0x20000
	s_addc_u32 s23, s23, 0
	s_mov_b32 m0, s37
	v_lshl_add_u64 v[222:223], s[22:23], 0, v[130:131]
	ds_read_b128 v[182:185], v147 offset:32768
	ds_read_b128 v[186:189], v147 offset:33792
	ds_read_b128 v[190:193], v147 offset:34816
	ds_read_b128 v[194:197], v147 offset:35840
	ds_read_b128 v[198:201], v147 offset:36864
	ds_read_b128 v[202:205], v147 offset:37888
	ds_read_b128 v[206:209], v147 offset:38912
	ds_read_b128 v[210:213], v147 offset:39936
	global_load_lds_dwordx4 v[222:223], off
	v_lshl_add_u64 v[222:223], s[22:23], 0, v[134:135]
	s_mov_b32 m0, s38
	s_nop 0
	global_load_lds_dwordx4 v[222:223], off
	s_waitcnt vmcnt(8)
	s_waitcnt lgkmcnt(0)
	s_barrier
	s_setprio 1
	s_waitcnt lgkmcnt(0)
	v_mfma_f32_16x16x32_bf16 v[126:129], v[150:153], v[182:185], v[126:129]
	v_mfma_f32_16x16x32_bf16 v[122:125], v[158:161], v[182:185], v[122:125]
	v_mfma_f32_16x16x32_bf16 v[118:121], v[150:153], v[190:193], v[118:121]
	v_mfma_f32_16x16x32_bf16 v[110:113], v[158:161], v[190:193], v[110:113]
	v_mfma_f32_16x16x32_bf16 v[102:105], v[150:153], v[198:201], v[102:105]
	v_mfma_f32_16x16x32_bf16 v[94:97], v[158:161], v[198:201], v[94:97]
	v_mfma_f32_16x16x32_bf16 v[86:89], v[150:153], v[206:209], v[86:89]
	v_mfma_f32_16x16x32_bf16 v[78:81], v[158:161], v[206:209], v[78:81]
	v_mfma_f32_16x16x32_bf16 v[126:129], v[154:157], v[186:189], v[126:129]
	v_mfma_f32_16x16x32_bf16 v[122:125], v[162:165], v[186:189], v[122:125]
	v_mfma_f32_16x16x32_bf16 v[118:121], v[154:157], v[194:197], v[118:121]
	v_mfma_f32_16x16x32_bf16 v[110:113], v[162:165], v[194:197], v[110:113]
	v_mfma_f32_16x16x32_bf16 v[102:105], v[154:157], v[202:205], v[102:105]
	v_mfma_f32_16x16x32_bf16 v[94:97], v[162:165], v[202:205], v[94:97]
	v_mfma_f32_16x16x32_bf16 v[86:89], v[154:157], v[210:213], v[86:89]
	v_mfma_f32_16x16x32_bf16 v[78:81], v[162:165], v[210:213], v[78:81]
	v_mfma_f32_16x16x32_bf16 v[114:117], v[166:169], v[182:185], v[114:117]
	v_mfma_f32_16x16x32_bf16 v[106:109], v[174:177], v[182:185], v[106:109]
	v_mfma_f32_16x16x32_bf16 v[98:101], v[166:169], v[190:193], v[98:101]
	v_mfma_f32_16x16x32_bf16 v[90:93], v[174:177], v[190:193], v[90:93]
	v_mfma_f32_16x16x32_bf16 v[82:85], v[166:169], v[198:201], v[82:85]
	v_mfma_f32_16x16x32_bf16 v[74:77], v[174:177], v[198:201], v[74:77]
	v_mfma_f32_16x16x32_bf16 v[70:73], v[166:169], v[206:209], v[70:73]
	v_mfma_f32_16x16x32_bf16 v[66:69], v[174:177], v[206:209], v[66:69]
	v_mfma_f32_16x16x32_bf16 v[114:117], v[170:173], v[186:189], v[114:117]
	v_mfma_f32_16x16x32_bf16 v[106:109], v[178:181], v[186:189], v[106:109]
	v_mfma_f32_16x16x32_bf16 v[98:101], v[170:173], v[194:197], v[98:101]
	v_mfma_f32_16x16x32_bf16 v[90:93], v[178:181], v[194:197], v[90:93]
	v_mfma_f32_16x16x32_bf16 v[82:85], v[170:173], v[202:205], v[82:85]
	v_mfma_f32_16x16x32_bf16 v[74:77], v[178:181], v[202:205], v[74:77]
	v_mfma_f32_16x16x32_bf16 v[70:73], v[170:173], v[210:213], v[70:73]
	v_mfma_f32_16x16x32_bf16 v[66:69], v[178:181], v[210:213], v[66:69]
	s_setprio 0
	s_barrier
	s_mov_b32 m0, s50
	v_lshl_add_u64 v[214:215], v[214:215], 0, s[12:13]
	s_add_u32 s18, s18, 0x20080
	ds_read_b128 v[182:185], v147 offset:49152
	ds_read_b128 v[186:189], v147 offset:50176
	ds_read_b128 v[190:193], v147 offset:51200
	ds_read_b128 v[194:197], v147 offset:52224
	ds_read_b128 v[198:201], v147 offset:53248
	ds_read_b128 v[202:205], v147 offset:54272
	ds_read_b128 v[206:209], v147 offset:55296
	ds_read_b128 v[210:213], v147 offset:56320
	global_load_lds_dwordx4 v[214:215], off
	v_lshl_add_u64 v[214:215], v[216:217], 0, s[12:13]
	s_mov_b32 m0, s51
	s_addc_u32 s19, s19, 0
	global_load_lds_dwordx4 v[214:215], off
	v_lshl_add_u64 v[214:215], s[18:19], 0, v[132:133]
	s_mov_b32 m0, s53
	s_nop 0
	global_load_lds_dwordx4 v[214:215], off
	v_lshl_add_u64 v[214:215], s[18:19], 0, v[136:137]
	s_mov_b32 m0, s54
	s_nop 0
	global_load_lds_dwordx4 v[214:215], off
	v_lshl_add_u64 v[214:215], v[218:219], 0, s[12:13]
	s_mov_b32 m0, s39
	s_nop 0
	global_load_lds_dwordx4 v[214:215], off
	v_lshl_add_u64 v[214:215], v[220:221], 0, s[12:13]
	s_mov_b32 m0, s40
	s_nop 0
	global_load_lds_dwordx4 v[214:215], off
	s_waitcnt vmcnt(8)
	s_waitcnt lgkmcnt(0)
	s_barrier
	s_setprio 1
	s_waitcnt lgkmcnt(0)
	v_mfma_f32_16x16x32_bf16 v[62:65], v[150:153], v[182:185], v[62:65]
	v_mfma_f32_16x16x32_bf16 v[58:61], v[158:161], v[182:185], v[58:61]
	v_mfma_f32_16x16x32_bf16 v[54:57], v[150:153], v[190:193], v[54:57]
	v_mfma_f32_16x16x32_bf16 v[46:49], v[158:161], v[190:193], v[46:49]
	v_mfma_f32_16x16x32_bf16 v[38:41], v[150:153], v[198:201], v[38:41]
	v_mfma_f32_16x16x32_bf16 v[30:33], v[158:161], v[198:201], v[30:33]
	v_mfma_f32_16x16x32_bf16 v[22:25], v[150:153], v[206:209], v[22:25]
	v_mfma_f32_16x16x32_bf16 v[14:17], v[158:161], v[206:209], v[14:17]
	v_mfma_f32_16x16x32_bf16 v[62:65], v[154:157], v[186:189], v[62:65]
	v_mfma_f32_16x16x32_bf16 v[58:61], v[162:165], v[186:189], v[58:61]
	v_mfma_f32_16x16x32_bf16 v[54:57], v[154:157], v[194:197], v[54:57]
	v_mfma_f32_16x16x32_bf16 v[46:49], v[162:165], v[194:197], v[46:49]
	v_mfma_f32_16x16x32_bf16 v[38:41], v[154:157], v[202:205], v[38:41]
	v_mfma_f32_16x16x32_bf16 v[30:33], v[162:165], v[202:205], v[30:33]
	v_mfma_f32_16x16x32_bf16 v[22:25], v[154:157], v[210:213], v[22:25]
	v_mfma_f32_16x16x32_bf16 v[14:17], v[162:165], v[210:213], v[14:17]
	v_mfma_f32_16x16x32_bf16 v[50:53], v[166:169], v[182:185], v[50:53]
	v_mfma_f32_16x16x32_bf16 v[42:45], v[174:177], v[182:185], v[42:45]
	v_mfma_f32_16x16x32_bf16 v[34:37], v[166:169], v[190:193], v[34:37]
	v_mfma_f32_16x16x32_bf16 v[26:29], v[174:177], v[190:193], v[26:29]
	v_mfma_f32_16x16x32_bf16 v[18:21], v[166:169], v[198:201], v[18:21]
	v_mfma_f32_16x16x32_bf16 v[10:13], v[174:177], v[198:201], v[10:13]
	v_mfma_f32_16x16x32_bf16 v[6:9], v[166:169], v[206:209], v[6:9]
	v_mfma_f32_16x16x32_bf16 v[2:5], v[174:177], v[206:209], v[2:5]
	v_mfma_f32_16x16x32_bf16 v[50:53], v[170:173], v[186:189], v[50:53]
	v_mfma_f32_16x16x32_bf16 v[42:45], v[178:181], v[186:189], v[42:45]
	v_mfma_f32_16x16x32_bf16 v[34:37], v[170:173], v[194:197], v[34:37]
	v_mfma_f32_16x16x32_bf16 v[26:29], v[178:181], v[194:197], v[26:29]
	v_mfma_f32_16x16x32_bf16 v[18:21], v[170:173], v[202:205], v[18:21]
	v_mfma_f32_16x16x32_bf16 v[10:13], v[178:181], v[202:205], v[10:13]
	v_mfma_f32_16x16x32_bf16 v[6:9], v[170:173], v[210:213], v[6:9]
	v_mfma_f32_16x16x32_bf16 v[2:5], v[178:181], v[210:213], v[2:5]
	s_setprio 0
	s_barrier
	s_add_i32 s43, s43, 2
	s_add_u32 s16, s16, 0x100
	s_addc_u32 s17, s17, 0
	s_cmp_gt_u32 s43, 5
	s_cbranch_scc0 .LBB0_268
	s_cmpk_lt_u32 s33, 0x100
	s_cbranch_scc0 .LBB0_271
	s_barrier

.LBB0_274:
	ds_read_b128 v[150:153], v144
	ds_read_b128 v[154:157], v144 offset:1024
	ds_read_b128 v[158:161], v144 offset:2048
	ds_read_b128 v[162:165], v144 offset:3072
	ds_read_b128 v[166:169], v145
	ds_read_b128 v[170:173], v145 offset:1024
	ds_read_b128 v[174:177], v145 offset:2048
	ds_read_b128 v[178:181], v145 offset:3072
	s_add_u32 s18, s14, s16
	s_addc_u32 s19, s15, s17
	s_add_u32 s18, s18, 0xf900100
	s_addc_u32 s19, s19, 0
	s_add_u32 s49, s40, s16
	s_addc_u32 s50, s41, s17
	s_cmpk_eq_i32 s16, 0x300
	s_cselect_b32 s23, s11, s19
	s_cselect_b32 s22, s10, s18
	s_cselect_b32 s19, s9, s50
	s_cselect_b32 s18, s8, s49
	s_mov_b32 m0, s43
	v_lshl_add_u64 v[214:215], v[140:141], 0, s[16:17]
	ds_read_b128 v[182:185], v146
	ds_read_b128 v[186:189], v146 offset:1024
	ds_read_b128 v[190:193], v146 offset:2048
	ds_read_b128 v[194:197], v146 offset:3072
	ds_read_b128 v[198:201], v146 offset:4096
	ds_read_b128 v[202:205], v146 offset:5120
	ds_read_b128 v[206:209], v146 offset:6144
	ds_read_b128 v[210:213], v146 offset:7168
	global_load_lds_dwordx4 v[214:215], off
	v_lshl_add_u64 v[214:215], v[138:139], 0, s[16:17]
	s_mov_b32 m0, s44
	s_nop 0
	global_load_lds_dwordx4 v[214:215], off
	s_waitcnt vmcnt(8)
	s_waitcnt lgkmcnt(0)
	s_barrier
	s_setprio 1
	s_waitcnt lgkmcnt(0)
	v_mfma_f32_16x16x32_bf16 v[126:129], v[150:153], v[182:185], v[126:129]
	v_mfma_f32_16x16x32_bf16 v[122:125], v[158:161], v[182:185], v[122:125]
	v_mfma_f32_16x16x32_bf16 v[118:121], v[150:153], v[190:193], v[118:121]
	v_mfma_f32_16x16x32_bf16 v[110:113], v[158:161], v[190:193], v[110:113]
	v_mfma_f32_16x16x32_bf16 v[102:105], v[150:153], v[198:201], v[102:105]
	v_mfma_f32_16x16x32_bf16 v[94:97], v[158:161], v[198:201], v[94:97]
	v_mfma_f32_16x16x32_bf16 v[86:89], v[150:153], v[206:209], v[86:89]
	v_mfma_f32_16x16x32_bf16 v[78:81], v[158:161], v[206:209], v[78:81]
	v_mfma_f32_16x16x32_bf16 v[126:129], v[154:157], v[186:189], v[126:129]
	v_mfma_f32_16x16x32_bf16 v[122:125], v[162:165], v[186:189], v[122:125]
	v_mfma_f32_16x16x32_bf16 v[118:121], v[154:157], v[194:197], v[118:121]
	v_mfma_f32_16x16x32_bf16 v[110:113], v[162:165], v[194:197], v[110:113]
	v_mfma_f32_16x16x32_bf16 v[102:105], v[154:157], v[202:205], v[102:105]
	v_mfma_f32_16x16x32_bf16 v[94:97], v[162:165], v[202:205], v[94:97]
	v_mfma_f32_16x16x32_bf16 v[86:89], v[154:157], v[210:213], v[86:89]
	v_mfma_f32_16x16x32_bf16 v[78:81], v[162:165], v[210:213], v[78:81]
	v_mfma_f32_16x16x32_bf16 v[114:117], v[166:169], v[182:185], v[114:117]
	v_mfma_f32_16x16x32_bf16 v[106:109], v[174:177], v[182:185], v[106:109]
	v_mfma_f32_16x16x32_bf16 v[98:101], v[166:169], v[190:193], v[98:101]
	v_mfma_f32_16x16x32_bf16 v[90:93], v[174:177], v[190:193], v[90:93]
	v_mfma_f32_16x16x32_bf16 v[82:85], v[166:169], v[198:201], v[82:85]
	v_mfma_f32_16x16x32_bf16 v[74:77], v[174:177], v[198:201], v[74:77]
	v_mfma_f32_16x16x32_bf16 v[70:73], v[166:169], v[206:209], v[70:73]
	v_mfma_f32_16x16x32_bf16 v[66:69], v[174:177], v[206:209], v[66:69]
	v_mfma_f32_16x16x32_bf16 v[114:117], v[170:173], v[186:189], v[114:117]
	v_mfma_f32_16x16x32_bf16 v[106:109], v[178:181], v[186:189], v[106:109]
	v_mfma_f32_16x16x32_bf16 v[98:101], v[170:173], v[194:197], v[98:101]
	v_mfma_f32_16x16x32_bf16 v[90:93], v[178:181], v[194:197], v[90:93]
	v_mfma_f32_16x16x32_bf16 v[82:85], v[170:173], v[202:205], v[82:85]
	v_mfma_f32_16x16x32_bf16 v[74:77], v[178:181], v[202:205], v[74:77]
	v_mfma_f32_16x16x32_bf16 v[70:73], v[170:173], v[210:213], v[70:73]
	v_mfma_f32_16x16x32_bf16 v[66:69], v[178:181], v[210:213], v[66:69]
	s_setprio 0
	s_barrier
	s_mov_b32 m0, s25
	v_lshl_add_u64 v[214:215], s[18:19], 0, v[130:131]
	s_add_u32 s50, s18, 0x20000
	ds_read_b128 v[182:185], v146 offset:16384
	ds_read_b128 v[186:189], v146 offset:17408
	ds_read_b128 v[190:193], v146 offset:18432
	ds_read_b128 v[194:197], v146 offset:19456
	ds_read_b128 v[198:201], v146 offset:20480
	ds_read_b128 v[202:205], v146 offset:21504
	ds_read_b128 v[206:209], v146 offset:22528
	ds_read_b128 v[210:213], v146 offset:23552
	global_load_lds_dwordx4 v[214:215], off
	v_lshl_add_u64 v[216:217], s[18:19], 0, v[136:137]
	s_mov_b32 m0, s45
	s_addc_u32 s51, s19, 0
	global_load_lds_dwordx4 v[216:217], off
	v_lshl_add_u64 v[218:219], s[50:51], 0, v[130:131]
	s_mov_b32 m0, s26
	v_lshl_add_u64 v[220:221], s[22:23], 0, v[134:135]
	global_load_lds_dwordx4 v[218:219], off
	v_lshl_add_u64 v[218:219], s[50:51], 0, v[136:137]
	s_mov_b32 m0, s46
	s_nop 0
	global_load_lds_dwordx4 v[218:219], off
	v_lshl_add_u64 v[218:219], s[22:23], 0, v[132:133]
	s_mov_b32 m0, s7
	s_nop 0
	global_load_lds_dwordx4 v[218:219], off
	s_mov_b32 m0, s34
	s_nop 0
	global_load_lds_dwordx4 v[220:221], off
	s_waitcnt vmcnt(8)
	s_waitcnt lgkmcnt(0)
	s_barrier
	s_setprio 1
	s_waitcnt lgkmcnt(0)
	v_mfma_f32_16x16x32_bf16 v[62:65], v[150:153], v[182:185], v[62:65]
	v_mfma_f32_16x16x32_bf16 v[58:61], v[158:161], v[182:185], v[58:61]
	v_mfma_f32_16x16x32_bf16 v[54:57], v[150:153], v[190:193], v[54:57]
	v_mfma_f32_16x16x32_bf16 v[46:49], v[158:161], v[190:193], v[46:49]
	v_mfma_f32_16x16x32_bf16 v[38:41], v[150:153], v[198:201], v[38:41]
	v_mfma_f32_16x16x32_bf16 v[30:33], v[158:161], v[198:201], v[30:33]
	v_mfma_f32_16x16x32_bf16 v[22:25], v[150:153], v[206:209], v[22:25]
	v_mfma_f32_16x16x32_bf16 v[14:17], v[158:161], v[206:209], v[14:17]
	v_mfma_f32_16x16x32_bf16 v[62:65], v[154:157], v[186:189], v[62:65]
	v_mfma_f32_16x16x32_bf16 v[58:61], v[162:165], v[186:189], v[58:61]
	v_mfma_f32_16x16x32_bf16 v[54:57], v[154:157], v[194:197], v[54:57]
	v_mfma_f32_16x16x32_bf16 v[46:49], v[162:165], v[194:197], v[46:49]
	v_mfma_f32_16x16x32_bf16 v[38:41], v[154:157], v[202:205], v[38:41]
	v_mfma_f32_16x16x32_bf16 v[30:33], v[162:165], v[202:205], v[30:33]
	v_mfma_f32_16x16x32_bf16 v[22:25], v[154:157], v[210:213], v[22:25]
	v_mfma_f32_16x16x32_bf16 v[14:17], v[162:165], v[210:213], v[14:17]
	v_mfma_f32_16x16x32_bf16 v[50:53], v[166:169], v[182:185], v[50:53]
	v_mfma_f32_16x16x32_bf16 v[42:45], v[174:177], v[182:185], v[42:45]
	v_mfma_f32_16x16x32_bf16 v[34:37], v[166:169], v[190:193], v[34:37]
	v_mfma_f32_16x16x32_bf16 v[26:29], v[174:177], v[190:193], v[26:29]
	v_mfma_f32_16x16x32_bf16 v[18:21], v[166:169], v[198:201], v[18:21]
	v_mfma_f32_16x16x32_bf16 v[10:13], v[174:177], v[198:201], v[10:13]
	v_mfma_f32_16x16x32_bf16 v[6:9], v[166:169], v[206:209], v[6:9]
	v_mfma_f32_16x16x32_bf16 v[2:5], v[174:177], v[206:209], v[2:5]
	v_mfma_f32_16x16x32_bf16 v[50:53], v[170:173], v[186:189], v[50:53]
	v_mfma_f32_16x16x32_bf16 v[42:45], v[178:181], v[186:189], v[42:45]
	v_mfma_f32_16x16x32_bf16 v[34:37], v[170:173], v[194:197], v[34:37]
	v_mfma_f32_16x16x32_bf16 v[26:29], v[178:181], v[194:197], v[26:29]
	v_mfma_f32_16x16x32_bf16 v[18:21], v[170:173], v[202:205], v[18:21]
	v_mfma_f32_16x16x32_bf16 v[10:13], v[178:181], v[202:205], v[10:13]
	v_mfma_f32_16x16x32_bf16 v[6:9], v[170:173], v[210:213], v[6:9]
	v_mfma_f32_16x16x32_bf16 v[2:5], v[178:181], v[210:213], v[2:5]
	s_setprio 0
	s_barrier
	ds_read_b128 v[150:153], v147
	ds_read_b128 v[154:157], v147 offset:1024
	ds_read_b128 v[158:161], v147 offset:2048
	ds_read_b128 v[162:165], v147 offset:3072
	ds_read_b128 v[166:169], v148
	ds_read_b128 v[170:173], v148 offset:1024
	ds_read_b128 v[174:177], v148 offset:2048
	ds_read_b128 v[178:181], v148 offset:3072
	s_add_u32 s22, s22, 0x20000
	s_addc_u32 s23, s23, 0
	s_mov_b32 m0, s35
	v_lshl_add_u64 v[222:223], s[22:23], 0, v[132:133]
	ds_read_b128 v[182:185], v146 offset:32768
	ds_read_b128 v[186:189], v146 offset:33792
	ds_read_b128 v[190:193], v146 offset:34816
	ds_read_b128 v[194:197], v146 offset:35840
	ds_read_b128 v[198:201], v146 offset:36864
	ds_read_b128 v[202:205], v146 offset:37888
	ds_read_b128 v[206:209], v146 offset:38912
	ds_read_b128 v[210:213], v146 offset:39936
	global_load_lds_dwordx4 v[222:223], off
	v_lshl_add_u64 v[222:223], s[22:23], 0, v[134:135]
	s_mov_b32 m0, s36
	s_nop 0
	global_load_lds_dwordx4 v[222:223], off
	s_waitcnt vmcnt(8)
	s_waitcnt lgkmcnt(0)
	s_barrier
	s_setprio 1
	s_waitcnt lgkmcnt(0)
	v_mfma_f32_16x16x32_bf16 v[126:129], v[150:153], v[182:185], v[126:129]
	v_mfma_f32_16x16x32_bf16 v[122:125], v[158:161], v[182:185], v[122:125]
	v_mfma_f32_16x16x32_bf16 v[118:121], v[150:153], v[190:193], v[118:121]
	v_mfma_f32_16x16x32_bf16 v[110:113], v[158:161], v[190:193], v[110:113]
	v_mfma_f32_16x16x32_bf16 v[102:105], v[150:153], v[198:201], v[102:105]
	v_mfma_f32_16x16x32_bf16 v[94:97], v[158:161], v[198:201], v[94:97]
	v_mfma_f32_16x16x32_bf16 v[86:89], v[150:153], v[206:209], v[86:89]
	v_mfma_f32_16x16x32_bf16 v[78:81], v[158:161], v[206:209], v[78:81]
	v_mfma_f32_16x16x32_bf16 v[126:129], v[154:157], v[186:189], v[126:129]
	v_mfma_f32_16x16x32_bf16 v[122:125], v[162:165], v[186:189], v[122:125]
	v_mfma_f32_16x16x32_bf16 v[118:121], v[154:157], v[194:197], v[118:121]
	v_mfma_f32_16x16x32_bf16 v[110:113], v[162:165], v[194:197], v[110:113]
	v_mfma_f32_16x16x32_bf16 v[102:105], v[154:157], v[202:205], v[102:105]
	v_mfma_f32_16x16x32_bf16 v[94:97], v[162:165], v[202:205], v[94:97]
	v_mfma_f32_16x16x32_bf16 v[86:89], v[154:157], v[210:213], v[86:89]
	v_mfma_f32_16x16x32_bf16 v[78:81], v[162:165], v[210:213], v[78:81]
	v_mfma_f32_16x16x32_bf16 v[114:117], v[166:169], v[182:185], v[114:117]
	v_mfma_f32_16x16x32_bf16 v[106:109], v[174:177], v[182:185], v[106:109]
	v_mfma_f32_16x16x32_bf16 v[98:101], v[166:169], v[190:193], v[98:101]
	v_mfma_f32_16x16x32_bf16 v[90:93], v[174:177], v[190:193], v[90:93]
	v_mfma_f32_16x16x32_bf16 v[82:85], v[166:169], v[198:201], v[82:85]
	v_mfma_f32_16x16x32_bf16 v[74:77], v[174:177], v[198:201], v[74:77]
	v_mfma_f32_16x16x32_bf16 v[70:73], v[166:169], v[206:209], v[70:73]
	v_mfma_f32_16x16x32_bf16 v[66:69], v[174:177], v[206:209], v[66:69]
	v_mfma_f32_16x16x32_bf16 v[114:117], v[170:173], v[186:189], v[114:117]
	v_mfma_f32_16x16x32_bf16 v[106:109], v[178:181], v[186:189], v[106:109]
	v_mfma_f32_16x16x32_bf16 v[98:101], v[170:173], v[194:197], v[98:101]
	v_mfma_f32_16x16x32_bf16 v[90:93], v[178:181], v[194:197], v[90:93]
	v_mfma_f32_16x16x32_bf16 v[82:85], v[170:173], v[202:205], v[82:85]
	v_mfma_f32_16x16x32_bf16 v[74:77], v[178:181], v[202:205], v[74:77]
	v_mfma_f32_16x16x32_bf16 v[70:73], v[170:173], v[210:213], v[70:73]
	v_mfma_f32_16x16x32_bf16 v[66:69], v[178:181], v[210:213], v[66:69]
	s_setprio 0
	s_barrier
	s_mov_b32 m0, s27
	v_lshl_add_u64 v[214:215], v[214:215], 0, s[12:13]
	s_add_u32 s18, s18, 0x20080
	ds_read_b128 v[182:185], v146 offset:49152
	ds_read_b128 v[186:189], v146 offset:50176
	ds_read_b128 v[190:193], v146 offset:51200
	ds_read_b128 v[194:197], v146 offset:52224
	ds_read_b128 v[198:201], v146 offset:53248
	ds_read_b128 v[202:205], v146 offset:54272
	ds_read_b128 v[206:209], v146 offset:55296
	ds_read_b128 v[210:213], v146 offset:56320
	global_load_lds_dwordx4 v[214:215], off
	v_lshl_add_u64 v[214:215], v[216:217], 0, s[12:13]
	s_mov_b32 m0, s47
	s_addc_u32 s19, s19, 0
	global_load_lds_dwordx4 v[214:215], off
	v_lshl_add_u64 v[214:215], s[18:19], 0, v[130:131]
	s_mov_b32 m0, s30
	s_nop 0
	global_load_lds_dwordx4 v[214:215], off
	v_lshl_add_u64 v[214:215], s[18:19], 0, v[136:137]
	s_mov_b32 m0, s48
	s_nop 0
	global_load_lds_dwordx4 v[214:215], off
	v_lshl_add_u64 v[214:215], v[218:219], 0, s[12:13]
	s_mov_b32 m0, s38
	s_nop 0
	global_load_lds_dwordx4 v[214:215], off
	v_lshl_add_u64 v[214:215], v[220:221], 0, s[12:13]
	s_mov_b32 m0, s39
	s_nop 0
	global_load_lds_dwordx4 v[214:215], off
	s_waitcnt vmcnt(8)
	s_waitcnt lgkmcnt(0)
	s_barrier
	s_setprio 1
	s_waitcnt lgkmcnt(0)
	v_mfma_f32_16x16x32_bf16 v[62:65], v[150:153], v[182:185], v[62:65]
	v_mfma_f32_16x16x32_bf16 v[58:61], v[158:161], v[182:185], v[58:61]
	v_mfma_f32_16x16x32_bf16 v[54:57], v[150:153], v[190:193], v[54:57]
	v_mfma_f32_16x16x32_bf16 v[46:49], v[158:161], v[190:193], v[46:49]
	v_mfma_f32_16x16x32_bf16 v[38:41], v[150:153], v[198:201], v[38:41]
	v_mfma_f32_16x16x32_bf16 v[30:33], v[158:161], v[198:201], v[30:33]
	v_mfma_f32_16x16x32_bf16 v[22:25], v[150:153], v[206:209], v[22:25]
	v_mfma_f32_16x16x32_bf16 v[14:17], v[158:161], v[206:209], v[14:17]
	v_mfma_f32_16x16x32_bf16 v[62:65], v[154:157], v[186:189], v[62:65]
	v_mfma_f32_16x16x32_bf16 v[58:61], v[162:165], v[186:189], v[58:61]
	v_mfma_f32_16x16x32_bf16 v[54:57], v[154:157], v[194:197], v[54:57]
	v_mfma_f32_16x16x32_bf16 v[46:49], v[162:165], v[194:197], v[46:49]
	v_mfma_f32_16x16x32_bf16 v[38:41], v[154:157], v[202:205], v[38:41]
	v_mfma_f32_16x16x32_bf16 v[30:33], v[162:165], v[202:205], v[30:33]
	v_mfma_f32_16x16x32_bf16 v[22:25], v[154:157], v[210:213], v[22:25]
	v_mfma_f32_16x16x32_bf16 v[14:17], v[162:165], v[210:213], v[14:17]
	v_mfma_f32_16x16x32_bf16 v[50:53], v[166:169], v[182:185], v[50:53]
	v_mfma_f32_16x16x32_bf16 v[42:45], v[174:177], v[182:185], v[42:45]
	v_mfma_f32_16x16x32_bf16 v[34:37], v[166:169], v[190:193], v[34:37]
	v_mfma_f32_16x16x32_bf16 v[26:29], v[174:177], v[190:193], v[26:29]
	v_mfma_f32_16x16x32_bf16 v[18:21], v[166:169], v[198:201], v[18:21]
	v_mfma_f32_16x16x32_bf16 v[10:13], v[174:177], v[198:201], v[10:13]
	v_mfma_f32_16x16x32_bf16 v[6:9], v[166:169], v[206:209], v[6:9]
	v_mfma_f32_16x16x32_bf16 v[2:5], v[174:177], v[206:209], v[2:5]
	v_mfma_f32_16x16x32_bf16 v[50:53], v[170:173], v[186:189], v[50:53]
	v_mfma_f32_16x16x32_bf16 v[42:45], v[178:181], v[186:189], v[42:45]
	v_mfma_f32_16x16x32_bf16 v[34:37], v[170:173], v[194:197], v[34:37]
	v_mfma_f32_16x16x32_bf16 v[26:29], v[178:181], v[194:197], v[26:29]
	v_mfma_f32_16x16x32_bf16 v[18:21], v[170:173], v[202:205], v[18:21]
	v_mfma_f32_16x16x32_bf16 v[10:13], v[178:181], v[202:205], v[10:13]
	v_mfma_f32_16x16x32_bf16 v[6:9], v[170:173], v[210:213], v[6:9]
	v_mfma_f32_16x16x32_bf16 v[2:5], v[178:181], v[210:213], v[2:5]
	s_setprio 0
	s_barrier
	s_add_i32 s42, s42, 2
	s_add_u32 s16, s16, 0x100
	s_addc_u32 s17, s17, 0
	s_cmp_gt_u32 s42, 5
	s_cbranch_scc0 .LBB0_274
	s_cmpk_lt_u32 s31, 0x100
	s_cbranch_scc0 .LBB0_277
	s_barrier

.LBB0_741:
	s_add_u32 s12, s36, 0xfff80080
	s_addc_u32 s13, s37, -1
	s_add_i32 s14, 0, 0x10000
	s_cmp_eq_u32 s11, 28
	s_cselect_b32 s63, s5, s13
	s_cselect_b32 s62, s6, s12
	s_cselect_b32 s39, s7, s10
	s_cselect_b32 s38, s8, s9
	s_add_i32 s15, 0, 0x14000
	v_add_u32_e32 v144, s14, v230
	v_add_u32_e32 v160, s15, v230
	ds_read_b128 v[124:127], v144
	ds_read_b128 v[128:131], v144 offset:1024
	ds_read_b128 v[136:139], v144 offset:2048
	ds_read_b128 v[144:147], v144 offset:3072
	ds_read_b128 v[148:151], v160
	ds_read_b128 v[152:155], v160 offset:1024
	ds_read_b128 v[156:159], v160 offset:2048
	ds_read_b128 v[160:163], v160 offset:3072
	v_lshl_add_u64 v[196:197], s[36:37], 0, v[222:223]
	s_add_i32 m0, s21, 0xc000
	ds_read_b128 v[164:167], v243
	ds_read_b128 v[168:171], v243 offset:1024
	ds_read_b128 v[172:175], v243 offset:2048
	ds_read_b128 v[176:179], v243 offset:3072
	ds_read_b128 v[180:183], v243 offset:4096
	ds_read_b128 v[184:187], v243 offset:5120
	ds_read_b128 v[188:191], v243 offset:6144
	ds_read_b128 v[192:195], v243 offset:7168
	global_load_lds_dwordx4 v[196:197], off
	v_lshl_add_u64 v[196:197], s[36:37], 0, v[220:221]
	s_add_i32 m0, s21, 0xe000
	s_nop 0
	global_load_lds_dwordx4 v[196:197], off
	s_waitcnt vmcnt(8)
	s_waitcnt lgkmcnt(0)
	s_barrier
	s_setprio 1
	s_waitcnt lgkmcnt(0)
	v_mfma_f32_16x16x32_bf16 v[140:143], v[124:127], v[164:167], v[140:143]
	v_mfma_f32_16x16x32_bf16 v[132:135], v[136:139], v[164:167], v[132:135]
	v_mfma_f32_16x16x32_bf16 v[112:115], v[124:127], v[172:175], v[112:115]
	v_mfma_f32_16x16x32_bf16 v[108:111], v[136:139], v[172:175], v[108:111]
	v_mfma_f32_16x16x32_bf16 v[96:99], v[124:127], v[180:183], v[96:99]
	v_mfma_f32_16x16x32_bf16 v[92:95], v[136:139], v[180:183], v[92:95]
	v_mfma_f32_16x16x32_bf16 v[80:83], v[124:127], v[188:191], v[80:83]
	v_mfma_f32_16x16x32_bf16 v[76:79], v[136:139], v[188:191], v[76:79]
	v_mfma_f32_16x16x32_bf16 v[140:143], v[128:131], v[168:171], v[140:143]
	v_mfma_f32_16x16x32_bf16 v[132:135], v[144:147], v[168:171], v[132:135]
	v_mfma_f32_16x16x32_bf16 v[112:115], v[128:131], v[176:179], v[112:115]
	v_mfma_f32_16x16x32_bf16 v[108:111], v[144:147], v[176:179], v[108:111]
	v_mfma_f32_16x16x32_bf16 v[96:99], v[128:131], v[184:187], v[96:99]
	v_mfma_f32_16x16x32_bf16 v[92:95], v[144:147], v[184:187], v[92:95]
	v_mfma_f32_16x16x32_bf16 v[80:83], v[128:131], v[192:195], v[80:83]
	v_mfma_f32_16x16x32_bf16 v[76:79], v[144:147], v[192:195], v[76:79]
	v_mfma_f32_16x16x32_bf16 v[120:123], v[148:151], v[164:167], v[120:123]
	v_mfma_f32_16x16x32_bf16 v[116:119], v[156:159], v[164:167], v[116:119]
	v_mfma_f32_16x16x32_bf16 v[104:107], v[148:151], v[172:175], v[104:107]
	v_mfma_f32_16x16x32_bf16 v[100:103], v[156:159], v[172:175], v[100:103]
	v_mfma_f32_16x16x32_bf16 v[88:91], v[148:151], v[180:183], v[88:91]
	v_mfma_f32_16x16x32_bf16 v[84:87], v[156:159], v[180:183], v[84:87]
	v_mfma_f32_16x16x32_bf16 v[72:75], v[148:151], v[188:191], v[72:75]
	v_mfma_f32_16x16x32_bf16 v[68:71], v[156:159], v[188:191], v[68:71]
	v_mfma_f32_16x16x32_bf16 v[120:123], v[152:155], v[168:171], v[120:123]
	v_mfma_f32_16x16x32_bf16 v[116:119], v[160:163], v[168:171], v[116:119]
	v_mfma_f32_16x16x32_bf16 v[104:107], v[152:155], v[176:179], v[104:107]
	v_mfma_f32_16x16x32_bf16 v[100:103], v[160:163], v[176:179], v[100:103]
	v_mfma_f32_16x16x32_bf16 v[88:91], v[152:155], v[184:187], v[88:91]
	v_mfma_f32_16x16x32_bf16 v[84:87], v[160:163], v[184:187], v[84:87]
	v_mfma_f32_16x16x32_bf16 v[72:75], v[152:155], v[192:195], v[72:75]
	v_mfma_f32_16x16x32_bf16 v[68:71], v[160:163], v[192:195], v[68:71]
	s_setprio 0
	s_barrier
	s_add_i32 s12, s14, s82
	v_lshl_add_u64 v[196:197], s[38:39], 0, v[2:3]
	s_mov_b32 m0, s12
	ds_read_b128 v[164:167], v243 offset:16384
	ds_read_b128 v[168:171], v243 offset:17408
	ds_read_b128 v[172:175], v243 offset:18432
	ds_read_b128 v[176:179], v243 offset:19456
	ds_read_b128 v[180:183], v243 offset:20480
	ds_read_b128 v[184:187], v243 offset:21504
	ds_read_b128 v[188:191], v243 offset:22528
	ds_read_b128 v[192:195], v243 offset:23552
	global_load_lds_dwordx4 v[196:197], off
	s_add_i32 m0, s12, 0x2000
	s_add_u32 s12, s38, 0x80000
	v_lshl_add_u64 v[198:199], s[38:39], 0, v[218:219]
	s_addc_u32 s13, s39, 0
	s_add_i32 s14, s15, s82
	global_load_lds_dwordx4 v[198:199], off
	v_lshl_add_u64 v[200:201], s[12:13], 0, v[2:3]
	s_mov_b32 m0, s14
	v_lshl_add_u64 v[202:203], s[62:63], 0, v[216:217]
	global_load_lds_dwordx4 v[200:201], off
	v_lshl_add_u64 v[200:201], s[12:13], 0, v[218:219]
	s_add_i32 m0, s14, 0x2000
	s_nop 0
	global_load_lds_dwordx4 v[200:201], off
	v_lshl_add_u64 v[200:201], s[62:63], 0, v[0:1]
	s_mov_b32 m0, s21
	s_nop 0
	global_load_lds_dwordx4 v[200:201], off
	s_mov_b32 m0, s83
	s_nop 0
	global_load_lds_dwordx4 v[202:203], off
	s_waitcnt vmcnt(8)
	s_waitcnt lgkmcnt(0)
	s_barrier
	s_setprio 1
	s_waitcnt lgkmcnt(0)
	v_mfma_f32_16x16x32_bf16 v[64:67], v[124:127], v[164:167], v[64:67]
	v_mfma_f32_16x16x32_bf16 v[60:63], v[136:139], v[164:167], v[60:63]
	v_mfma_f32_16x16x32_bf16 v[48:51], v[124:127], v[172:175], v[48:51]
	v_mfma_f32_16x16x32_bf16 v[44:47], v[136:139], v[172:175], v[44:47]
	v_mfma_f32_16x16x32_bf16 v[32:35], v[124:127], v[180:183], v[32:35]
	v_mfma_f32_16x16x32_bf16 v[28:31], v[136:139], v[180:183], v[28:31]
	v_mfma_f32_16x16x32_bf16 v[16:19], v[124:127], v[188:191], v[16:19]
	v_mfma_f32_16x16x32_bf16 v[12:15], v[136:139], v[188:191], v[12:15]
	v_mfma_f32_16x16x32_bf16 v[64:67], v[128:131], v[168:171], v[64:67]
	v_mfma_f32_16x16x32_bf16 v[60:63], v[144:147], v[168:171], v[60:63]
	v_mfma_f32_16x16x32_bf16 v[48:51], v[128:131], v[176:179], v[48:51]
	v_mfma_f32_16x16x32_bf16 v[44:47], v[144:147], v[176:179], v[44:47]
	v_mfma_f32_16x16x32_bf16 v[32:35], v[128:131], v[184:187], v[32:35]
	v_mfma_f32_16x16x32_bf16 v[28:31], v[144:147], v[184:187], v[28:31]
	v_mfma_f32_16x16x32_bf16 v[16:19], v[128:131], v[192:195], v[16:19]
	v_mfma_f32_16x16x32_bf16 v[12:15], v[144:147], v[192:195], v[12:15]
	v_mfma_f32_16x16x32_bf16 v[56:59], v[148:151], v[164:167], v[56:59]
	v_mfma_f32_16x16x32_bf16 v[52:55], v[156:159], v[164:167], v[52:55]
	v_mfma_f32_16x16x32_bf16 v[40:43], v[148:151], v[172:175], v[40:43]
	v_mfma_f32_16x16x32_bf16 v[36:39], v[156:159], v[172:175], v[36:39]
	v_mfma_f32_16x16x32_bf16 v[24:27], v[148:151], v[180:183], v[24:27]
	v_mfma_f32_16x16x32_bf16 v[20:23], v[156:159], v[180:183], v[20:23]
	v_mfma_f32_16x16x32_bf16 v[8:11], v[148:151], v[188:191], v[8:11]
	v_mfma_f32_16x16x32_bf16 v[4:7], v[156:159], v[188:191], v[4:7]
	v_mfma_f32_16x16x32_bf16 v[56:59], v[152:155], v[168:171], v[56:59]
	v_mfma_f32_16x16x32_bf16 v[52:55], v[160:163], v[168:171], v[52:55]
	v_mfma_f32_16x16x32_bf16 v[40:43], v[152:155], v[176:179], v[40:43]
	v_mfma_f32_16x16x32_bf16 v[36:39], v[160:163], v[176:179], v[36:39]
	v_mfma_f32_16x16x32_bf16 v[24:27], v[152:155], v[184:187], v[24:27]
	v_mfma_f32_16x16x32_bf16 v[20:23], v[160:163], v[184:187], v[20:23]
	v_mfma_f32_16x16x32_bf16 v[8:11], v[152:155], v[192:195], v[8:11]
	v_mfma_f32_16x16x32_bf16 v[4:7], v[160:163], v[192:195], v[4:7]
	s_setprio 0
	s_barrier
	s_add_i32 s14, 0, 0x18000
	s_add_i32 s15, 0, 0x1c000
	v_add_u32_e32 v144, s14, v230
	v_add_u32_e32 v160, s15, v230
	ds_read_b128 v[124:127], v144
	ds_read_b128 v[128:131], v144 offset:1024
	ds_read_b128 v[136:139], v144 offset:2048
	ds_read_b128 v[144:147], v144 offset:3072
	ds_read_b128 v[148:151], v160
	ds_read_b128 v[152:155], v160 offset:1024
	ds_read_b128 v[156:159], v160 offset:2048
	ds_read_b128 v[160:163], v160 offset:3072
	s_add_u32 s12, s62, 0x80000
	s_addc_u32 s13, s63, 0
	s_mov_b32 m0, s84
	v_lshl_add_u64 v[204:205], s[12:13], 0, v[0:1]
	ds_read_b128 v[164:167], v243 offset:32768
	ds_read_b128 v[168:171], v243 offset:33792
	ds_read_b128 v[172:175], v243 offset:34816
	ds_read_b128 v[176:179], v243 offset:35840
	ds_read_b128 v[180:183], v243 offset:36864
	ds_read_b128 v[184:187], v243 offset:37888
	ds_read_b128 v[188:191], v243 offset:38912
	ds_read_b128 v[192:195], v243 offset:39936
	global_load_lds_dwordx4 v[204:205], off
	v_lshl_add_u64 v[204:205], s[12:13], 0, v[216:217]
	s_mov_b32 m0, s85
	s_nop 0
	global_load_lds_dwordx4 v[204:205], off
	s_waitcnt vmcnt(8)
	s_waitcnt lgkmcnt(0)
	s_barrier
	s_setprio 1
	s_waitcnt lgkmcnt(0)
	v_mfma_f32_16x16x32_bf16 v[140:143], v[124:127], v[164:167], v[140:143]
	v_mfma_f32_16x16x32_bf16 v[132:135], v[136:139], v[164:167], v[132:135]
	v_mfma_f32_16x16x32_bf16 v[112:115], v[124:127], v[172:175], v[112:115]
	v_mfma_f32_16x16x32_bf16 v[108:111], v[136:139], v[172:175], v[108:111]
	v_mfma_f32_16x16x32_bf16 v[96:99], v[124:127], v[180:183], v[96:99]
	v_mfma_f32_16x16x32_bf16 v[92:95], v[136:139], v[180:183], v[92:95]
	v_mfma_f32_16x16x32_bf16 v[80:83], v[124:127], v[188:191], v[80:83]
	v_mfma_f32_16x16x32_bf16 v[76:79], v[136:139], v[188:191], v[76:79]
	v_mfma_f32_16x16x32_bf16 v[140:143], v[128:131], v[168:171], v[140:143]
	v_mfma_f32_16x16x32_bf16 v[132:135], v[144:147], v[168:171], v[132:135]
	v_mfma_f32_16x16x32_bf16 v[112:115], v[128:131], v[176:179], v[112:115]
	v_mfma_f32_16x16x32_bf16 v[108:111], v[144:147], v[176:179], v[108:111]
	v_mfma_f32_16x16x32_bf16 v[96:99], v[128:131], v[184:187], v[96:99]
	v_mfma_f32_16x16x32_bf16 v[92:95], v[144:147], v[184:187], v[92:95]
	v_mfma_f32_16x16x32_bf16 v[80:83], v[128:131], v[192:195], v[80:83]
	v_mfma_f32_16x16x32_bf16 v[76:79], v[144:147], v[192:195], v[76:79]
	v_mfma_f32_16x16x32_bf16 v[120:123], v[148:151], v[164:167], v[120:123]
	v_mfma_f32_16x16x32_bf16 v[116:119], v[156:159], v[164:167], v[116:119]
	v_mfma_f32_16x16x32_bf16 v[104:107], v[148:151], v[172:175], v[104:107]
	v_mfma_f32_16x16x32_bf16 v[100:103], v[156:159], v[172:175], v[100:103]
	v_mfma_f32_16x16x32_bf16 v[88:91], v[148:151], v[180:183], v[88:91]
	v_mfma_f32_16x16x32_bf16 v[84:87], v[156:159], v[180:183], v[84:87]
	v_mfma_f32_16x16x32_bf16 v[72:75], v[148:151], v[188:191], v[72:75]
	v_mfma_f32_16x16x32_bf16 v[68:71], v[156:159], v[188:191], v[68:71]
	v_mfma_f32_16x16x32_bf16 v[120:123], v[152:155], v[168:171], v[120:123]
	v_mfma_f32_16x16x32_bf16 v[116:119], v[160:163], v[168:171], v[116:119]
	v_mfma_f32_16x16x32_bf16 v[104:107], v[152:155], v[176:179], v[104:107]
	v_mfma_f32_16x16x32_bf16 v[100:103], v[160:163], v[176:179], v[100:103]
	v_mfma_f32_16x16x32_bf16 v[88:91], v[152:155], v[184:187], v[88:91]
	v_mfma_f32_16x16x32_bf16 v[84:87], v[160:163], v[184:187], v[84:87]
	v_mfma_f32_16x16x32_bf16 v[72:75], v[152:155], v[192:195], v[72:75]
	v_mfma_f32_16x16x32_bf16 v[68:71], v[160:163], v[192:195], v[68:71]
	s_setprio 0
	s_barrier
	s_add_i32 s12, s14, s82
	v_lshl_add_u64 v[196:197], v[196:197], 0, s[68:69]
	s_mov_b32 m0, s12
	ds_read_b128 v[164:167], v243 offset:49152
	ds_read_b128 v[168:171], v243 offset:50176
	ds_read_b128 v[172:175], v243 offset:51200
	ds_read_b128 v[176:179], v243 offset:52224
	ds_read_b128 v[180:183], v243 offset:53248
	ds_read_b128 v[184:187], v243 offset:54272
	ds_read_b128 v[188:191], v243 offset:55296
	ds_read_b128 v[192:195], v243 offset:56320
	global_load_lds_dwordx4 v[196:197], off
	s_add_i32 m0, s12, 0x2000
	s_add_u32 s12, s38, 0x80080
	v_lshl_add_u64 v[196:197], v[198:199], 0, s[68:69]
	s_addc_u32 s13, s39, 0
	s_add_i32 s14, s15, s82
	global_load_lds_dwordx4 v[196:197], off
	v_lshl_add_u64 v[196:197], s[12:13], 0, v[2:3]
	s_mov_b32 m0, s14
	s_nop 0
	global_load_lds_dwordx4 v[196:197], off
	v_lshl_add_u64 v[196:197], s[12:13], 0, v[218:219]
	s_add_i32 m0, s14, 0x2000
	s_nop 0
	global_load_lds_dwordx4 v[196:197], off
	v_lshl_add_u64 v[196:197], v[200:201], 0, s[68:69]
	s_mov_b32 m0, s89
	s_nop 0
	global_load_lds_dwordx4 v[196:197], off
	v_lshl_add_u64 v[196:197], v[202:203], 0, s[68:69]
	s_mov_b32 m0, s90
	s_nop 0
	global_load_lds_dwordx4 v[196:197], off
	s_waitcnt vmcnt(8)
	s_waitcnt lgkmcnt(0)
	s_barrier
	s_setprio 1
	s_waitcnt lgkmcnt(0)
	v_mfma_f32_16x16x32_bf16 v[64:67], v[124:127], v[164:167], v[64:67]
	v_mfma_f32_16x16x32_bf16 v[60:63], v[136:139], v[164:167], v[60:63]
	v_mfma_f32_16x16x32_bf16 v[48:51], v[124:127], v[172:175], v[48:51]
	v_mfma_f32_16x16x32_bf16 v[44:47], v[136:139], v[172:175], v[44:47]
	v_mfma_f32_16x16x32_bf16 v[32:35], v[124:127], v[180:183], v[32:35]
	v_mfma_f32_16x16x32_bf16 v[28:31], v[136:139], v[180:183], v[28:31]
	v_mfma_f32_16x16x32_bf16 v[16:19], v[124:127], v[188:191], v[16:19]
	v_mfma_f32_16x16x32_bf16 v[12:15], v[136:139], v[188:191], v[12:15]
	v_mfma_f32_16x16x32_bf16 v[64:67], v[128:131], v[168:171], v[64:67]
	v_mfma_f32_16x16x32_bf16 v[60:63], v[144:147], v[168:171], v[60:63]
	v_mfma_f32_16x16x32_bf16 v[48:51], v[128:131], v[176:179], v[48:51]
	v_mfma_f32_16x16x32_bf16 v[44:47], v[144:147], v[176:179], v[44:47]
	v_mfma_f32_16x16x32_bf16 v[32:35], v[128:131], v[184:187], v[32:35]
	v_mfma_f32_16x16x32_bf16 v[28:31], v[144:147], v[184:187], v[28:31]
	v_mfma_f32_16x16x32_bf16 v[16:19], v[128:131], v[192:195], v[16:19]
	v_mfma_f32_16x16x32_bf16 v[12:15], v[144:147], v[192:195], v[12:15]
	v_mfma_f32_16x16x32_bf16 v[56:59], v[148:151], v[164:167], v[56:59]
	v_mfma_f32_16x16x32_bf16 v[52:55], v[156:159], v[164:167], v[52:55]
	v_mfma_f32_16x16x32_bf16 v[40:43], v[148:151], v[172:175], v[40:43]
	v_mfma_f32_16x16x32_bf16 v[36:39], v[156:159], v[172:175], v[36:39]
	v_mfma_f32_16x16x32_bf16 v[24:27], v[148:151], v[180:183], v[24:27]
	v_mfma_f32_16x16x32_bf16 v[20:23], v[156:159], v[180:183], v[20:23]
	v_mfma_f32_16x16x32_bf16 v[8:11], v[148:151], v[188:191], v[8:11]
	v_mfma_f32_16x16x32_bf16 v[4:7], v[156:159], v[188:191], v[4:7]
	v_mfma_f32_16x16x32_bf16 v[56:59], v[152:155], v[168:171], v[56:59]
	v_mfma_f32_16x16x32_bf16 v[52:55], v[160:163], v[168:171], v[52:55]
	v_mfma_f32_16x16x32_bf16 v[40:43], v[152:155], v[176:179], v[40:43]
	v_mfma_f32_16x16x32_bf16 v[36:39], v[160:163], v[176:179], v[36:39]
	v_mfma_f32_16x16x32_bf16 v[24:27], v[152:155], v[184:187], v[24:27]
	v_mfma_f32_16x16x32_bf16 v[20:23], v[160:163], v[184:187], v[20:23]
	v_mfma_f32_16x16x32_bf16 v[8:11], v[152:155], v[192:195], v[8:11]
	v_mfma_f32_16x16x32_bf16 v[4:7], v[160:163], v[192:195], v[4:7]
	s_setprio 0
	s_barrier
	s_add_i32 s11, s11, 2
	s_add_u32 s9, s9, 0x100
	s_addc_u32 s10, s10, 0
	s_add_u32 s36, s36, 0x100
	s_addc_u32 s37, s37, 0
	s_cmp_gt_u32 s11, 29
	s_cbranch_scc0 .LBB0_741
	s_and_b64 vcc, exec, s[46:47]
	s_cbranch_vccz .LBB0_744
	s_barrier

.LBB0_854:
	s_add_u32 s26, s18, s24
	s_addc_u32 s27, s19, s25
	s_add_u32 s26, s26, 0x22100100
	s_addc_u32 s27, s27, 0
	s_add_u32 s29, s16, s24
	s_addc_u32 s30, s17, s25
	s_add_i32 s31, 0, 0x10000
	s_cmpk_eq_i32 s24, 0xf00
	s_cselect_b32 s37, s23, s27
	s_cselect_b32 s36, s22, s26
	s_cselect_b32 s27, s21, s30
	s_cselect_b32 s26, s20, s29
	s_add_i32 s29, 0, 0x14000
	v_add_u32_e32 v154, s31, v140
	v_add_u32_e32 v170, s29, v140
	ds_read_b128 v[142:145], v154
	ds_read_b128 v[146:149], v154 offset:1024
	ds_read_b128 v[150:153], v154 offset:2048
	ds_read_b128 v[154:157], v154 offset:3072
	ds_read_b128 v[158:161], v170
	ds_read_b128 v[162:165], v170 offset:1024
	ds_read_b128 v[166:169], v170 offset:2048
	ds_read_b128 v[170:173], v170 offset:3072
	v_lshl_add_u64 v[198:199], v[138:139], 0, s[24:25]
	s_add_i32 m0, s10, 0xc000
	ds_read_b128 v[174:177], v141
	ds_read_b128 v[178:181], v141 offset:1024
	ds_read_b128 v[182:185], v141 offset:2048
	ds_read_b128 v[186:189], v141 offset:3072
	ds_read_b128 v[190:193], v141 offset:4096
	ds_read_b128 v[194:197], v141 offset:5120
	ds_read_b128 v[204:207], v141 offset:6144
	ds_read_b128 v[208:211], v141 offset:7168
	global_load_lds_dwordx4 v[198:199], off
	v_lshl_add_u64 v[198:199], v[136:137], 0, s[24:25]
	s_add_i32 m0, s10, 0xe000
	s_nop 0
	global_load_lds_dwordx4 v[198:199], off
	s_waitcnt vmcnt(8)
	s_waitcnt lgkmcnt(0)
	s_barrier
	s_setprio 1
	s_waitcnt lgkmcnt(0)
	v_mfma_f32_16x16x32_bf16 v[128:131], v[142:145], v[174:177], v[128:131]
	v_mfma_f32_16x16x32_bf16 v[124:127], v[150:153], v[174:177], v[124:127]
	v_mfma_f32_16x16x32_bf16 v[112:115], v[142:145], v[182:185], v[112:115]
	v_mfma_f32_16x16x32_bf16 v[108:111], v[150:153], v[182:185], v[108:111]
	v_mfma_f32_16x16x32_bf16 v[96:99], v[142:145], v[190:193], v[96:99]
	v_mfma_f32_16x16x32_bf16 v[92:95], v[150:153], v[190:193], v[92:95]
	v_mfma_f32_16x16x32_bf16 v[80:83], v[142:145], v[204:207], v[80:83]
	v_mfma_f32_16x16x32_bf16 v[76:79], v[150:153], v[204:207], v[76:79]
	v_mfma_f32_16x16x32_bf16 v[128:131], v[146:149], v[178:181], v[128:131]
	v_mfma_f32_16x16x32_bf16 v[124:127], v[154:157], v[178:181], v[124:127]
	v_mfma_f32_16x16x32_bf16 v[112:115], v[146:149], v[186:189], v[112:115]
	v_mfma_f32_16x16x32_bf16 v[108:111], v[154:157], v[186:189], v[108:111]
	v_mfma_f32_16x16x32_bf16 v[96:99], v[146:149], v[194:197], v[96:99]
	v_mfma_f32_16x16x32_bf16 v[92:95], v[154:157], v[194:197], v[92:95]
	v_mfma_f32_16x16x32_bf16 v[80:83], v[146:149], v[208:211], v[80:83]
	v_mfma_f32_16x16x32_bf16 v[76:79], v[154:157], v[208:211], v[76:79]
	v_mfma_f32_16x16x32_bf16 v[120:123], v[158:161], v[174:177], v[120:123]
	v_mfma_f32_16x16x32_bf16 v[116:119], v[166:169], v[174:177], v[116:119]
	v_mfma_f32_16x16x32_bf16 v[104:107], v[158:161], v[182:185], v[104:107]
	v_mfma_f32_16x16x32_bf16 v[100:103], v[166:169], v[182:185], v[100:103]
	v_mfma_f32_16x16x32_bf16 v[88:91], v[158:161], v[190:193], v[88:91]
	v_mfma_f32_16x16x32_bf16 v[84:87], v[166:169], v[190:193], v[84:87]
	v_mfma_f32_16x16x32_bf16 v[72:75], v[158:161], v[204:207], v[72:75]
	v_mfma_f32_16x16x32_bf16 v[68:71], v[166:169], v[204:207], v[68:71]
	v_mfma_f32_16x16x32_bf16 v[120:123], v[162:165], v[178:181], v[120:123]
	v_mfma_f32_16x16x32_bf16 v[116:119], v[170:173], v[178:181], v[116:119]
	v_mfma_f32_16x16x32_bf16 v[104:107], v[162:165], v[186:189], v[104:107]
	v_mfma_f32_16x16x32_bf16 v[100:103], v[170:173], v[186:189], v[100:103]
	v_mfma_f32_16x16x32_bf16 v[88:91], v[162:165], v[194:197], v[88:91]
	v_mfma_f32_16x16x32_bf16 v[84:87], v[170:173], v[194:197], v[84:87]
	v_mfma_f32_16x16x32_bf16 v[72:75], v[162:165], v[208:211], v[72:75]
	v_mfma_f32_16x16x32_bf16 v[68:71], v[170:173], v[208:211], v[68:71]
	s_setprio 0
	s_barrier
	s_add_i32 s30, s31, s9
	v_lshl_add_u64 v[198:199], s[26:27], 0, v[2:3]
	s_mov_b32 m0, s30
	ds_read_b128 v[174:177], v141 offset:16384
	ds_read_b128 v[178:181], v141 offset:17408
	ds_read_b128 v[182:185], v141 offset:18432
	ds_read_b128 v[186:189], v141 offset:19456
	ds_read_b128 v[190:193], v141 offset:20480
	ds_read_b128 v[194:197], v141 offset:21504
	ds_read_b128 v[204:207], v141 offset:22528
	ds_read_b128 v[208:211], v141 offset:23552
	global_load_lds_dwordx4 v[198:199], off
	s_add_i32 m0, s30, 0x2000
	s_add_u32 s30, s26, 0x80000
	v_lshl_add_u64 v[212:213], s[26:27], 0, v[134:135]
	s_addc_u32 s31, s27, 0
	s_add_i32 s29, s29, s9
	global_load_lds_dwordx4 v[212:213], off
	v_lshl_add_u64 v[214:215], s[30:31], 0, v[2:3]
	s_mov_b32 m0, s29
	v_lshl_add_u64 v[216:217], s[36:37], 0, v[132:133]
	global_load_lds_dwordx4 v[214:215], off
	v_lshl_add_u64 v[214:215], s[30:31], 0, v[134:135]
	s_add_i32 m0, s29, 0x2000
	s_nop 0
	global_load_lds_dwordx4 v[214:215], off
	v_lshl_add_u64 v[214:215], s[36:37], 0, v[0:1]
	s_mov_b32 m0, s10
	s_nop 0
	global_load_lds_dwordx4 v[214:215], off
	s_mov_b32 m0, s11
	s_nop 0
	global_load_lds_dwordx4 v[216:217], off
	s_waitcnt vmcnt(8)
	s_waitcnt lgkmcnt(0)
	s_barrier
	s_setprio 1
	s_waitcnt lgkmcnt(0)
	v_mfma_f32_16x16x32_bf16 v[64:67], v[142:145], v[174:177], v[64:67]
	v_mfma_f32_16x16x32_bf16 v[60:63], v[150:153], v[174:177], v[60:63]
	v_mfma_f32_16x16x32_bf16 v[48:51], v[142:145], v[182:185], v[48:51]
	v_mfma_f32_16x16x32_bf16 v[44:47], v[150:153], v[182:185], v[44:47]
	v_mfma_f32_16x16x32_bf16 v[32:35], v[142:145], v[190:193], v[32:35]
	v_mfma_f32_16x16x32_bf16 v[28:31], v[150:153], v[190:193], v[28:31]
	v_mfma_f32_16x16x32_bf16 v[16:19], v[142:145], v[204:207], v[16:19]
	v_mfma_f32_16x16x32_bf16 v[12:15], v[150:153], v[204:207], v[12:15]
	v_mfma_f32_16x16x32_bf16 v[64:67], v[146:149], v[178:181], v[64:67]
	v_mfma_f32_16x16x32_bf16 v[60:63], v[154:157], v[178:181], v[60:63]
	v_mfma_f32_16x16x32_bf16 v[48:51], v[146:149], v[186:189], v[48:51]
	v_mfma_f32_16x16x32_bf16 v[44:47], v[154:157], v[186:189], v[44:47]
	v_mfma_f32_16x16x32_bf16 v[32:35], v[146:149], v[194:197], v[32:35]
	v_mfma_f32_16x16x32_bf16 v[28:31], v[154:157], v[194:197], v[28:31]
	v_mfma_f32_16x16x32_bf16 v[16:19], v[146:149], v[208:211], v[16:19]
	v_mfma_f32_16x16x32_bf16 v[12:15], v[154:157], v[208:211], v[12:15]
	v_mfma_f32_16x16x32_bf16 v[56:59], v[158:161], v[174:177], v[56:59]
	v_mfma_f32_16x16x32_bf16 v[52:55], v[166:169], v[174:177], v[52:55]
	v_mfma_f32_16x16x32_bf16 v[40:43], v[158:161], v[182:185], v[40:43]
	v_mfma_f32_16x16x32_bf16 v[36:39], v[166:169], v[182:185], v[36:39]
	v_mfma_f32_16x16x32_bf16 v[24:27], v[158:161], v[190:193], v[24:27]
	v_mfma_f32_16x16x32_bf16 v[20:23], v[166:169], v[190:193], v[20:23]
	v_mfma_f32_16x16x32_bf16 v[8:11], v[158:161], v[204:207], v[8:11]
	v_mfma_f32_16x16x32_bf16 v[4:7], v[166:169], v[204:207], v[4:7]
	v_mfma_f32_16x16x32_bf16 v[56:59], v[162:165], v[178:181], v[56:59]
	v_mfma_f32_16x16x32_bf16 v[52:55], v[170:173], v[178:181], v[52:55]
	v_mfma_f32_16x16x32_bf16 v[40:43], v[162:165], v[186:189], v[40:43]
	v_mfma_f32_16x16x32_bf16 v[36:39], v[170:173], v[186:189], v[36:39]
	v_mfma_f32_16x16x32_bf16 v[24:27], v[162:165], v[194:197], v[24:27]
	v_mfma_f32_16x16x32_bf16 v[20:23], v[170:173], v[194:197], v[20:23]
	v_mfma_f32_16x16x32_bf16 v[8:11], v[162:165], v[208:211], v[8:11]
	v_mfma_f32_16x16x32_bf16 v[4:7], v[170:173], v[208:211], v[4:7]
	s_setprio 0
	s_barrier
	s_add_i32 s29, 0, 0x18000
	s_add_i32 s33, 0, 0x1c000
	v_add_u32_e32 v154, s29, v140
	v_add_u32_e32 v170, s33, v140
	ds_read_b128 v[142:145], v154
	ds_read_b128 v[146:149], v154 offset:1024
	ds_read_b128 v[150:153], v154 offset:2048
	ds_read_b128 v[154:157], v154 offset:3072
	ds_read_b128 v[158:161], v170
	ds_read_b128 v[162:165], v170 offset:1024
	ds_read_b128 v[166:169], v170 offset:2048
	ds_read_b128 v[170:173], v170 offset:3072
	s_add_u32 s30, s36, 0x80000
	s_addc_u32 s31, s37, 0
	s_mov_b32 m0, s12
	v_lshl_add_u64 v[218:219], s[30:31], 0, v[0:1]
	ds_read_b128 v[174:177], v141 offset:32768
	ds_read_b128 v[178:181], v141 offset:33792
	ds_read_b128 v[182:185], v141 offset:34816
	ds_read_b128 v[186:189], v141 offset:35840
	ds_read_b128 v[190:193], v141 offset:36864
	ds_read_b128 v[194:197], v141 offset:37888
	ds_read_b128 v[204:207], v141 offset:38912
	ds_read_b128 v[208:211], v141 offset:39936
	global_load_lds_dwordx4 v[218:219], off
	v_lshl_add_u64 v[218:219], s[30:31], 0, v[132:133]
	s_mov_b32 m0, s13
	s_nop 0
	global_load_lds_dwordx4 v[218:219], off
	s_waitcnt vmcnt(8)
	s_waitcnt lgkmcnt(0)
	s_barrier
	s_setprio 1
	s_waitcnt lgkmcnt(0)
	v_mfma_f32_16x16x32_bf16 v[128:131], v[142:145], v[174:177], v[128:131]
	v_mfma_f32_16x16x32_bf16 v[124:127], v[150:153], v[174:177], v[124:127]
	v_mfma_f32_16x16x32_bf16 v[112:115], v[142:145], v[182:185], v[112:115]
	v_mfma_f32_16x16x32_bf16 v[108:111], v[150:153], v[182:185], v[108:111]
	v_mfma_f32_16x16x32_bf16 v[96:99], v[142:145], v[190:193], v[96:99]
	v_mfma_f32_16x16x32_bf16 v[92:95], v[150:153], v[190:193], v[92:95]
	v_mfma_f32_16x16x32_bf16 v[80:83], v[142:145], v[204:207], v[80:83]
	v_mfma_f32_16x16x32_bf16 v[76:79], v[150:153], v[204:207], v[76:79]
	v_mfma_f32_16x16x32_bf16 v[128:131], v[146:149], v[178:181], v[128:131]
	v_mfma_f32_16x16x32_bf16 v[124:127], v[154:157], v[178:181], v[124:127]
	v_mfma_f32_16x16x32_bf16 v[112:115], v[146:149], v[186:189], v[112:115]
	v_mfma_f32_16x16x32_bf16 v[108:111], v[154:157], v[186:189], v[108:111]
	v_mfma_f32_16x16x32_bf16 v[96:99], v[146:149], v[194:197], v[96:99]
	v_mfma_f32_16x16x32_bf16 v[92:95], v[154:157], v[194:197], v[92:95]
	v_mfma_f32_16x16x32_bf16 v[80:83], v[146:149], v[208:211], v[80:83]
	v_mfma_f32_16x16x32_bf16 v[76:79], v[154:157], v[208:211], v[76:79]
	v_mfma_f32_16x16x32_bf16 v[120:123], v[158:161], v[174:177], v[120:123]
	v_mfma_f32_16x16x32_bf16 v[116:119], v[166:169], v[174:177], v[116:119]
	v_mfma_f32_16x16x32_bf16 v[104:107], v[158:161], v[182:185], v[104:107]
	v_mfma_f32_16x16x32_bf16 v[100:103], v[166:169], v[182:185], v[100:103]
	v_mfma_f32_16x16x32_bf16 v[88:91], v[158:161], v[190:193], v[88:91]
	v_mfma_f32_16x16x32_bf16 v[84:87], v[166:169], v[190:193], v[84:87]
	v_mfma_f32_16x16x32_bf16 v[72:75], v[158:161], v[204:207], v[72:75]
	v_mfma_f32_16x16x32_bf16 v[68:71], v[166:169], v[204:207], v[68:71]
	v_mfma_f32_16x16x32_bf16 v[120:123], v[162:165], v[178:181], v[120:123]
	v_mfma_f32_16x16x32_bf16 v[116:119], v[170:173], v[178:181], v[116:119]
	v_mfma_f32_16x16x32_bf16 v[104:107], v[162:165], v[186:189], v[104:107]
	v_mfma_f32_16x16x32_bf16 v[100:103], v[170:173], v[186:189], v[100:103]
	v_mfma_f32_16x16x32_bf16 v[88:91], v[162:165], v[194:197], v[88:91]
	v_mfma_f32_16x16x32_bf16 v[84:87], v[170:173], v[194:197], v[84:87]
	v_mfma_f32_16x16x32_bf16 v[72:75], v[162:165], v[208:211], v[72:75]
	v_mfma_f32_16x16x32_bf16 v[68:71], v[170:173], v[208:211], v[68:71]
	s_setprio 0
	s_barrier
	s_add_i32 s29, s29, s9
	v_lshl_add_u64 v[198:199], v[198:199], 0, s[68:69]
	s_mov_b32 m0, s29
	ds_read_b128 v[174:177], v141 offset:49152
	ds_read_b128 v[178:181], v141 offset:50176
	ds_read_b128 v[182:185], v141 offset:51200
	ds_read_b128 v[186:189], v141 offset:52224
	ds_read_b128 v[190:193], v141 offset:53248
	ds_read_b128 v[194:197], v141 offset:54272
	ds_read_b128 v[204:207], v141 offset:55296
	ds_read_b128 v[208:211], v141 offset:56320
	global_load_lds_dwordx4 v[198:199], off
	s_add_i32 m0, s29, 0x2000
	s_add_u32 s26, s26, 0x80080
	v_lshl_add_u64 v[198:199], v[212:213], 0, s[68:69]
	s_addc_u32 s27, s27, 0
	s_add_i32 s29, s33, s9
	global_load_lds_dwordx4 v[198:199], off
	v_lshl_add_u64 v[198:199], s[26:27], 0, v[2:3]
	s_mov_b32 m0, s29
	s_nop 0
	global_load_lds_dwordx4 v[198:199], off
	v_lshl_add_u64 v[198:199], s[26:27], 0, v[134:135]
	s_add_i32 m0, s29, 0x2000
	s_nop 0
	global_load_lds_dwordx4 v[198:199], off
	v_lshl_add_u64 v[198:199], v[214:215], 0, s[68:69]
	s_mov_b32 m0, s14
	s_nop 0
	global_load_lds_dwordx4 v[198:199], off
	v_lshl_add_u64 v[198:199], v[216:217], 0, s[68:69]
	s_mov_b32 m0, s15
	s_nop 0
	global_load_lds_dwordx4 v[198:199], off
	s_waitcnt vmcnt(8)
	s_waitcnt lgkmcnt(0)
	s_barrier
	s_setprio 1
	s_waitcnt lgkmcnt(0)
	v_mfma_f32_16x16x32_bf16 v[64:67], v[142:145], v[174:177], v[64:67]
	v_mfma_f32_16x16x32_bf16 v[60:63], v[150:153], v[174:177], v[60:63]
	v_mfma_f32_16x16x32_bf16 v[48:51], v[142:145], v[182:185], v[48:51]
	v_mfma_f32_16x16x32_bf16 v[44:47], v[150:153], v[182:185], v[44:47]
	v_mfma_f32_16x16x32_bf16 v[32:35], v[142:145], v[190:193], v[32:35]
	v_mfma_f32_16x16x32_bf16 v[28:31], v[150:153], v[190:193], v[28:31]
	v_mfma_f32_16x16x32_bf16 v[16:19], v[142:145], v[204:207], v[16:19]
	v_mfma_f32_16x16x32_bf16 v[12:15], v[150:153], v[204:207], v[12:15]
	v_mfma_f32_16x16x32_bf16 v[64:67], v[146:149], v[178:181], v[64:67]
	v_mfma_f32_16x16x32_bf16 v[60:63], v[154:157], v[178:181], v[60:63]
	v_mfma_f32_16x16x32_bf16 v[48:51], v[146:149], v[186:189], v[48:51]
	v_mfma_f32_16x16x32_bf16 v[44:47], v[154:157], v[186:189], v[44:47]
	v_mfma_f32_16x16x32_bf16 v[32:35], v[146:149], v[194:197], v[32:35]
	v_mfma_f32_16x16x32_bf16 v[28:31], v[154:157], v[194:197], v[28:31]
	v_mfma_f32_16x16x32_bf16 v[16:19], v[146:149], v[208:211], v[16:19]
	v_mfma_f32_16x16x32_bf16 v[12:15], v[154:157], v[208:211], v[12:15]
	v_mfma_f32_16x16x32_bf16 v[56:59], v[158:161], v[174:177], v[56:59]
	v_mfma_f32_16x16x32_bf16 v[52:55], v[166:169], v[174:177], v[52:55]
	v_mfma_f32_16x16x32_bf16 v[40:43], v[158:161], v[182:185], v[40:43]
	v_mfma_f32_16x16x32_bf16 v[36:39], v[166:169], v[182:185], v[36:39]
	v_mfma_f32_16x16x32_bf16 v[24:27], v[158:161], v[190:193], v[24:27]
	v_mfma_f32_16x16x32_bf16 v[20:23], v[166:169], v[190:193], v[20:23]
	v_mfma_f32_16x16x32_bf16 v[8:11], v[158:161], v[204:207], v[8:11]
	v_mfma_f32_16x16x32_bf16 v[4:7], v[166:169], v[204:207], v[4:7]
	v_mfma_f32_16x16x32_bf16 v[56:59], v[162:165], v[178:181], v[56:59]
	v_mfma_f32_16x16x32_bf16 v[52:55], v[170:173], v[178:181], v[52:55]
	v_mfma_f32_16x16x32_bf16 v[40:43], v[162:165], v[186:189], v[40:43]
	v_mfma_f32_16x16x32_bf16 v[36:39], v[170:173], v[186:189], v[36:39]
	v_mfma_f32_16x16x32_bf16 v[24:27], v[162:165], v[194:197], v[24:27]
	v_mfma_f32_16x16x32_bf16 v[20:23], v[170:173], v[194:197], v[20:23]
	v_mfma_f32_16x16x32_bf16 v[8:11], v[162:165], v[208:211], v[8:11]
	v_mfma_f32_16x16x32_bf16 v[4:7], v[170:173], v[208:211], v[4:7]
	s_setprio 0
	s_barrier
	s_add_i32 s28, s28, 2
	s_add_u32 s24, s24, 0x100
	s_addc_u32 s25, s25, 0
	s_cmp_lt_u32 s28, 30
	s_cbranch_scc1 .LBB0_854
	s_waitcnt vmcnt(0)
	s_cmpk_gt_u32 s6, 0xff
	s_cbranch_scc1 .LBB0_857
	s_barrier

.LBB0_947:
	s_add_u32 s12, s38, 0xfffc0080
	s_addc_u32 s13, s39, -1
	s_add_i32 s14, 0, 0x10000
	s_cmp_eq_u32 s11, 12
	s_cselect_b32 s57, s5, s13
	s_cselect_b32 s56, s6, s12
	s_cselect_b32 s41, s7, s10
	s_cselect_b32 s40, s8, s9
	s_add_i32 s15, 0, 0x14000
	v_add_u32_e32 v144, s14, v230
	v_add_u32_e32 v160, s15, v230
	ds_read_b128 v[124:127], v144
	ds_read_b128 v[128:131], v144 offset:1024
	ds_read_b128 v[136:139], v144 offset:2048
	ds_read_b128 v[144:147], v144 offset:3072
	ds_read_b128 v[148:151], v160
	ds_read_b128 v[152:155], v160 offset:1024
	ds_read_b128 v[156:159], v160 offset:2048
	ds_read_b128 v[160:163], v160 offset:3072
	v_lshl_add_u64 v[196:197], s[38:39], 0, v[222:223]
	s_add_i32 m0, s71, 0xc000
	ds_read_b128 v[164:167], v243
	ds_read_b128 v[168:171], v243 offset:1024
	ds_read_b128 v[172:175], v243 offset:2048
	ds_read_b128 v[176:179], v243 offset:3072
	ds_read_b128 v[180:183], v243 offset:4096
	ds_read_b128 v[184:187], v243 offset:5120
	ds_read_b128 v[188:191], v243 offset:6144
	ds_read_b128 v[192:195], v243 offset:7168
	global_load_lds_dwordx4 v[196:197], off
	v_lshl_add_u64 v[196:197], s[38:39], 0, v[220:221]
	s_add_i32 m0, s71, 0xe000
	s_nop 0
	global_load_lds_dwordx4 v[196:197], off
	s_waitcnt vmcnt(8)
	s_waitcnt lgkmcnt(0)
	s_barrier
	s_setprio 1
	s_waitcnt lgkmcnt(0)
	v_mfma_f32_16x16x32_bf16 v[140:143], v[124:127], v[164:167], v[140:143]
	v_mfma_f32_16x16x32_bf16 v[132:135], v[136:139], v[164:167], v[132:135]
	v_mfma_f32_16x16x32_bf16 v[112:115], v[124:127], v[172:175], v[112:115]
	v_mfma_f32_16x16x32_bf16 v[108:111], v[136:139], v[172:175], v[108:111]
	v_mfma_f32_16x16x32_bf16 v[96:99], v[124:127], v[180:183], v[96:99]
	v_mfma_f32_16x16x32_bf16 v[92:95], v[136:139], v[180:183], v[92:95]
	v_mfma_f32_16x16x32_bf16 v[80:83], v[124:127], v[188:191], v[80:83]
	v_mfma_f32_16x16x32_bf16 v[76:79], v[136:139], v[188:191], v[76:79]
	v_mfma_f32_16x16x32_bf16 v[140:143], v[128:131], v[168:171], v[140:143]
	v_mfma_f32_16x16x32_bf16 v[132:135], v[144:147], v[168:171], v[132:135]
	v_mfma_f32_16x16x32_bf16 v[112:115], v[128:131], v[176:179], v[112:115]
	v_mfma_f32_16x16x32_bf16 v[108:111], v[144:147], v[176:179], v[108:111]
	v_mfma_f32_16x16x32_bf16 v[96:99], v[128:131], v[184:187], v[96:99]
	v_mfma_f32_16x16x32_bf16 v[92:95], v[144:147], v[184:187], v[92:95]
	v_mfma_f32_16x16x32_bf16 v[80:83], v[128:131], v[192:195], v[80:83]
	v_mfma_f32_16x16x32_bf16 v[76:79], v[144:147], v[192:195], v[76:79]
	v_mfma_f32_16x16x32_bf16 v[120:123], v[148:151], v[164:167], v[120:123]
	v_mfma_f32_16x16x32_bf16 v[116:119], v[156:159], v[164:167], v[116:119]
	v_mfma_f32_16x16x32_bf16 v[104:107], v[148:151], v[172:175], v[104:107]
	v_mfma_f32_16x16x32_bf16 v[100:103], v[156:159], v[172:175], v[100:103]
	v_mfma_f32_16x16x32_bf16 v[88:91], v[148:151], v[180:183], v[88:91]
	v_mfma_f32_16x16x32_bf16 v[84:87], v[156:159], v[180:183], v[84:87]
	v_mfma_f32_16x16x32_bf16 v[72:75], v[148:151], v[188:191], v[72:75]
	v_mfma_f32_16x16x32_bf16 v[68:71], v[156:159], v[188:191], v[68:71]
	v_mfma_f32_16x16x32_bf16 v[120:123], v[152:155], v[168:171], v[120:123]
	v_mfma_f32_16x16x32_bf16 v[116:119], v[160:163], v[168:171], v[116:119]
	v_mfma_f32_16x16x32_bf16 v[104:107], v[152:155], v[176:179], v[104:107]
	v_mfma_f32_16x16x32_bf16 v[100:103], v[160:163], v[176:179], v[100:103]
	v_mfma_f32_16x16x32_bf16 v[88:91], v[152:155], v[184:187], v[88:91]
	v_mfma_f32_16x16x32_bf16 v[84:87], v[160:163], v[184:187], v[84:87]
	v_mfma_f32_16x16x32_bf16 v[72:75], v[152:155], v[192:195], v[72:75]
	v_mfma_f32_16x16x32_bf16 v[68:71], v[160:163], v[192:195], v[68:71]
	s_setprio 0
	s_barrier
	s_add_i32 s12, s14, s70
	v_lshl_add_u64 v[196:197], s[40:41], 0, v[2:3]
	s_mov_b32 m0, s12
	ds_read_b128 v[164:167], v243 offset:16384
	ds_read_b128 v[168:171], v243 offset:17408
	ds_read_b128 v[172:175], v243 offset:18432
	ds_read_b128 v[176:179], v243 offset:19456
	ds_read_b128 v[180:183], v243 offset:20480
	ds_read_b128 v[184:187], v243 offset:21504
	ds_read_b128 v[188:191], v243 offset:22528
	ds_read_b128 v[192:195], v243 offset:23552
	global_load_lds_dwordx4 v[196:197], off
	s_add_i32 m0, s12, 0x2000
	s_add_u32 s12, s40, 0x40000
	v_lshl_add_u64 v[198:199], s[40:41], 0, v[218:219]
	s_addc_u32 s13, s41, 0
	s_add_i32 s14, s15, s70
	global_load_lds_dwordx4 v[198:199], off
	v_lshl_add_u64 v[200:201], s[12:13], 0, v[2:3]
	s_mov_b32 m0, s14
	v_lshl_add_u64 v[202:203], s[56:57], 0, v[216:217]
	global_load_lds_dwordx4 v[200:201], off
	v_lshl_add_u64 v[200:201], s[12:13], 0, v[218:219]
	s_add_i32 m0, s14, 0x2000
	s_nop 0
	global_load_lds_dwordx4 v[200:201], off
	v_lshl_add_u64 v[200:201], s[56:57], 0, v[0:1]
	s_mov_b32 m0, s71
	s_nop 0
	global_load_lds_dwordx4 v[200:201], off
	s_mov_b32 m0, s80
	s_nop 0
	global_load_lds_dwordx4 v[202:203], off
	s_waitcnt vmcnt(8)
	s_waitcnt lgkmcnt(0)
	s_barrier
	s_setprio 1
	s_waitcnt lgkmcnt(0)
	v_mfma_f32_16x16x32_bf16 v[64:67], v[124:127], v[164:167], v[64:67]
	v_mfma_f32_16x16x32_bf16 v[60:63], v[136:139], v[164:167], v[60:63]
	v_mfma_f32_16x16x32_bf16 v[48:51], v[124:127], v[172:175], v[48:51]
	v_mfma_f32_16x16x32_bf16 v[44:47], v[136:139], v[172:175], v[44:47]
	v_mfma_f32_16x16x32_bf16 v[32:35], v[124:127], v[180:183], v[32:35]
	v_mfma_f32_16x16x32_bf16 v[28:31], v[136:139], v[180:183], v[28:31]
	v_mfma_f32_16x16x32_bf16 v[16:19], v[124:127], v[188:191], v[16:19]
	v_mfma_f32_16x16x32_bf16 v[12:15], v[136:139], v[188:191], v[12:15]
	v_mfma_f32_16x16x32_bf16 v[64:67], v[128:131], v[168:171], v[64:67]
	v_mfma_f32_16x16x32_bf16 v[60:63], v[144:147], v[168:171], v[60:63]
	v_mfma_f32_16x16x32_bf16 v[48:51], v[128:131], v[176:179], v[48:51]
	v_mfma_f32_16x16x32_bf16 v[44:47], v[144:147], v[176:179], v[44:47]
	v_mfma_f32_16x16x32_bf16 v[32:35], v[128:131], v[184:187], v[32:35]
	v_mfma_f32_16x16x32_bf16 v[28:31], v[144:147], v[184:187], v[28:31]
	v_mfma_f32_16x16x32_bf16 v[16:19], v[128:131], v[192:195], v[16:19]
	v_mfma_f32_16x16x32_bf16 v[12:15], v[144:147], v[192:195], v[12:15]
	v_mfma_f32_16x16x32_bf16 v[56:59], v[148:151], v[164:167], v[56:59]
	v_mfma_f32_16x16x32_bf16 v[52:55], v[156:159], v[164:167], v[52:55]
	v_mfma_f32_16x16x32_bf16 v[40:43], v[148:151], v[172:175], v[40:43]
	v_mfma_f32_16x16x32_bf16 v[36:39], v[156:159], v[172:175], v[36:39]
	v_mfma_f32_16x16x32_bf16 v[24:27], v[148:151], v[180:183], v[24:27]
	v_mfma_f32_16x16x32_bf16 v[20:23], v[156:159], v[180:183], v[20:23]
	v_mfma_f32_16x16x32_bf16 v[8:11], v[148:151], v[188:191], v[8:11]
	v_mfma_f32_16x16x32_bf16 v[4:7], v[156:159], v[188:191], v[4:7]
	v_mfma_f32_16x16x32_bf16 v[56:59], v[152:155], v[168:171], v[56:59]
	v_mfma_f32_16x16x32_bf16 v[52:55], v[160:163], v[168:171], v[52:55]
	v_mfma_f32_16x16x32_bf16 v[40:43], v[152:155], v[176:179], v[40:43]
	v_mfma_f32_16x16x32_bf16 v[36:39], v[160:163], v[176:179], v[36:39]
	v_mfma_f32_16x16x32_bf16 v[24:27], v[152:155], v[184:187], v[24:27]
	v_mfma_f32_16x16x32_bf16 v[20:23], v[160:163], v[184:187], v[20:23]
	v_mfma_f32_16x16x32_bf16 v[8:11], v[152:155], v[192:195], v[8:11]
	v_mfma_f32_16x16x32_bf16 v[4:7], v[160:163], v[192:195], v[4:7]
	s_setprio 0
	s_barrier
	s_add_i32 s14, 0, 0x18000
	s_add_i32 s15, 0, 0x1c000
	v_add_u32_e32 v144, s14, v230
	v_add_u32_e32 v160, s15, v230
	ds_read_b128 v[124:127], v144
	ds_read_b128 v[128:131], v144 offset:1024
	ds_read_b128 v[136:139], v144 offset:2048
	ds_read_b128 v[144:147], v144 offset:3072
	ds_read_b128 v[148:151], v160
	ds_read_b128 v[152:155], v160 offset:1024
	ds_read_b128 v[156:159], v160 offset:2048
	ds_read_b128 v[160:163], v160 offset:3072
	s_add_u32 s12, s56, 0x40000
	s_addc_u32 s13, s57, 0
	s_mov_b32 m0, s81
	v_lshl_add_u64 v[204:205], s[12:13], 0, v[0:1]
	ds_read_b128 v[164:167], v243 offset:32768
	ds_read_b128 v[168:171], v243 offset:33792
	ds_read_b128 v[172:175], v243 offset:34816
	ds_read_b128 v[176:179], v243 offset:35840
	ds_read_b128 v[180:183], v243 offset:36864
	ds_read_b128 v[184:187], v243 offset:37888
	ds_read_b128 v[188:191], v243 offset:38912
	ds_read_b128 v[192:195], v243 offset:39936
	global_load_lds_dwordx4 v[204:205], off
	v_lshl_add_u64 v[204:205], s[12:13], 0, v[216:217]
	s_mov_b32 m0, s82
	s_nop 0
	global_load_lds_dwordx4 v[204:205], off
	s_waitcnt vmcnt(8)
	s_waitcnt lgkmcnt(0)
	s_barrier
	s_setprio 1
	s_waitcnt lgkmcnt(0)
	v_mfma_f32_16x16x32_bf16 v[140:143], v[124:127], v[164:167], v[140:143]
	v_mfma_f32_16x16x32_bf16 v[132:135], v[136:139], v[164:167], v[132:135]
	v_mfma_f32_16x16x32_bf16 v[112:115], v[124:127], v[172:175], v[112:115]
	v_mfma_f32_16x16x32_bf16 v[108:111], v[136:139], v[172:175], v[108:111]
	v_mfma_f32_16x16x32_bf16 v[96:99], v[124:127], v[180:183], v[96:99]
	v_mfma_f32_16x16x32_bf16 v[92:95], v[136:139], v[180:183], v[92:95]
	v_mfma_f32_16x16x32_bf16 v[80:83], v[124:127], v[188:191], v[80:83]
	v_mfma_f32_16x16x32_bf16 v[76:79], v[136:139], v[188:191], v[76:79]
	v_mfma_f32_16x16x32_bf16 v[140:143], v[128:131], v[168:171], v[140:143]
	v_mfma_f32_16x16x32_bf16 v[132:135], v[144:147], v[168:171], v[132:135]
	v_mfma_f32_16x16x32_bf16 v[112:115], v[128:131], v[176:179], v[112:115]
	v_mfma_f32_16x16x32_bf16 v[108:111], v[144:147], v[176:179], v[108:111]
	v_mfma_f32_16x16x32_bf16 v[96:99], v[128:131], v[184:187], v[96:99]
	v_mfma_f32_16x16x32_bf16 v[92:95], v[144:147], v[184:187], v[92:95]
	v_mfma_f32_16x16x32_bf16 v[80:83], v[128:131], v[192:195], v[80:83]
	v_mfma_f32_16x16x32_bf16 v[76:79], v[144:147], v[192:195], v[76:79]
	v_mfma_f32_16x16x32_bf16 v[120:123], v[148:151], v[164:167], v[120:123]
	v_mfma_f32_16x16x32_bf16 v[116:119], v[156:159], v[164:167], v[116:119]
	v_mfma_f32_16x16x32_bf16 v[104:107], v[148:151], v[172:175], v[104:107]
	v_mfma_f32_16x16x32_bf16 v[100:103], v[156:159], v[172:175], v[100:103]
	v_mfma_f32_16x16x32_bf16 v[88:91], v[148:151], v[180:183], v[88:91]
	v_mfma_f32_16x16x32_bf16 v[84:87], v[156:159], v[180:183], v[84:87]
	v_mfma_f32_16x16x32_bf16 v[72:75], v[148:151], v[188:191], v[72:75]
	v_mfma_f32_16x16x32_bf16 v[68:71], v[156:159], v[188:191], v[68:71]
	v_mfma_f32_16x16x32_bf16 v[120:123], v[152:155], v[168:171], v[120:123]
	v_mfma_f32_16x16x32_bf16 v[116:119], v[160:163], v[168:171], v[116:119]
	v_mfma_f32_16x16x32_bf16 v[104:107], v[152:155], v[176:179], v[104:107]
	v_mfma_f32_16x16x32_bf16 v[100:103], v[160:163], v[176:179], v[100:103]
	v_mfma_f32_16x16x32_bf16 v[88:91], v[152:155], v[184:187], v[88:91]
	v_mfma_f32_16x16x32_bf16 v[84:87], v[160:163], v[184:187], v[84:87]
	v_mfma_f32_16x16x32_bf16 v[72:75], v[152:155], v[192:195], v[72:75]
	v_mfma_f32_16x16x32_bf16 v[68:71], v[160:163], v[192:195], v[68:71]
	s_setprio 0
	s_barrier
	s_add_i32 s12, s14, s70
	v_lshl_add_u64 v[196:197], v[196:197], 0, s[68:69]
	s_mov_b32 m0, s12
	ds_read_b128 v[164:167], v243 offset:49152
	ds_read_b128 v[168:171], v243 offset:50176
	ds_read_b128 v[172:175], v243 offset:51200
	ds_read_b128 v[176:179], v243 offset:52224
	ds_read_b128 v[180:183], v243 offset:53248
	ds_read_b128 v[184:187], v243 offset:54272
	ds_read_b128 v[188:191], v243 offset:55296
	ds_read_b128 v[192:195], v243 offset:56320
	global_load_lds_dwordx4 v[196:197], off
	s_add_i32 m0, s12, 0x2000
	s_add_u32 s12, s40, 0x40080
	v_lshl_add_u64 v[196:197], v[198:199], 0, s[68:69]
	s_addc_u32 s13, s41, 0
	s_add_i32 s14, s15, s70
	global_load_lds_dwordx4 v[196:197], off
	v_lshl_add_u64 v[196:197], s[12:13], 0, v[2:3]
	s_mov_b32 m0, s14
	s_nop 0
	global_load_lds_dwordx4 v[196:197], off
	v_lshl_add_u64 v[196:197], s[12:13], 0, v[218:219]
	s_add_i32 m0, s14, 0x2000
	s_nop 0
	global_load_lds_dwordx4 v[196:197], off
	v_lshl_add_u64 v[196:197], v[200:201], 0, s[68:69]
	s_mov_b32 m0, s85
	s_nop 0
	global_load_lds_dwordx4 v[196:197], off
	v_lshl_add_u64 v[196:197], v[202:203], 0, s[68:69]
	s_mov_b32 m0, s87
	s_nop 0
	global_load_lds_dwordx4 v[196:197], off
	s_waitcnt vmcnt(8)
	s_waitcnt lgkmcnt(0)
	s_barrier
	s_setprio 1
	s_waitcnt lgkmcnt(0)
	v_mfma_f32_16x16x32_bf16 v[64:67], v[124:127], v[164:167], v[64:67]
	v_mfma_f32_16x16x32_bf16 v[60:63], v[136:139], v[164:167], v[60:63]
	v_mfma_f32_16x16x32_bf16 v[48:51], v[124:127], v[172:175], v[48:51]
	v_mfma_f32_16x16x32_bf16 v[44:47], v[136:139], v[172:175], v[44:47]
	v_mfma_f32_16x16x32_bf16 v[32:35], v[124:127], v[180:183], v[32:35]
	v_mfma_f32_16x16x32_bf16 v[28:31], v[136:139], v[180:183], v[28:31]
	v_mfma_f32_16x16x32_bf16 v[16:19], v[124:127], v[188:191], v[16:19]
	v_mfma_f32_16x16x32_bf16 v[12:15], v[136:139], v[188:191], v[12:15]
	v_mfma_f32_16x16x32_bf16 v[64:67], v[128:131], v[168:171], v[64:67]
	v_mfma_f32_16x16x32_bf16 v[60:63], v[144:147], v[168:171], v[60:63]
	v_mfma_f32_16x16x32_bf16 v[48:51], v[128:131], v[176:179], v[48:51]
	v_mfma_f32_16x16x32_bf16 v[44:47], v[144:147], v[176:179], v[44:47]
	v_mfma_f32_16x16x32_bf16 v[32:35], v[128:131], v[184:187], v[32:35]
	v_mfma_f32_16x16x32_bf16 v[28:31], v[144:147], v[184:187], v[28:31]
	v_mfma_f32_16x16x32_bf16 v[16:19], v[128:131], v[192:195], v[16:19]
	v_mfma_f32_16x16x32_bf16 v[12:15], v[144:147], v[192:195], v[12:15]
	v_mfma_f32_16x16x32_bf16 v[56:59], v[148:151], v[164:167], v[56:59]
	v_mfma_f32_16x16x32_bf16 v[52:55], v[156:159], v[164:167], v[52:55]
	v_mfma_f32_16x16x32_bf16 v[40:43], v[148:151], v[172:175], v[40:43]
	v_mfma_f32_16x16x32_bf16 v[36:39], v[156:159], v[172:175], v[36:39]
	v_mfma_f32_16x16x32_bf16 v[24:27], v[148:151], v[180:183], v[24:27]
	v_mfma_f32_16x16x32_bf16 v[20:23], v[156:159], v[180:183], v[20:23]
	v_mfma_f32_16x16x32_bf16 v[8:11], v[148:151], v[188:191], v[8:11]
	v_mfma_f32_16x16x32_bf16 v[4:7], v[156:159], v[188:191], v[4:7]
	v_mfma_f32_16x16x32_bf16 v[56:59], v[152:155], v[168:171], v[56:59]
	v_mfma_f32_16x16x32_bf16 v[52:55], v[160:163], v[168:171], v[52:55]
	v_mfma_f32_16x16x32_bf16 v[40:43], v[152:155], v[176:179], v[40:43]
	v_mfma_f32_16x16x32_bf16 v[36:39], v[160:163], v[176:179], v[36:39]
	v_mfma_f32_16x16x32_bf16 v[24:27], v[152:155], v[184:187], v[24:27]
	v_mfma_f32_16x16x32_bf16 v[20:23], v[160:163], v[184:187], v[20:23]
	v_mfma_f32_16x16x32_bf16 v[8:11], v[152:155], v[192:195], v[8:11]
	v_mfma_f32_16x16x32_bf16 v[4:7], v[160:163], v[192:195], v[4:7]
	s_setprio 0
	s_barrier
	s_add_i32 s11, s11, 2
	s_add_u32 s9, s9, 0x100
	s_addc_u32 s10, s10, 0
	s_add_u32 s38, s38, 0x100
	s_addc_u32 s39, s39, 0
	s_cmp_gt_u32 s11, 13
	s_cbranch_scc0 .LBB0_947
	s_and_b64 vcc, exec, s[46:47]
	s_cbranch_vccz .LBB0_950
	s_barrier

.LBB0_1134:
	s_add_u32 s40, s38, 0x100
	s_addc_u32 s41, s39, 0
	s_add_i32 s8, 0, 0x10000
	s_cmpk_eq_i32 s7, 0x54
	s_cselect_b32 s45, s61, s41
	s_cselect_b32 s44, s60, s40
	s_cselect_b32 s43, s63, s6
	s_cselect_b32 s42, s62, s5
	s_add_i32 s10, 0, 0x14000
	v_add_u32_e32 v112, s8, v242
	v_add_u32_e32 v148, s10, v242
	ds_read_b128 v[92:95], v112
	ds_read_b128 v[100:103], v112 offset:1024
	ds_read_b128 v[108:111], v112 offset:2048
	ds_read_b128 v[112:115], v112 offset:3072
	ds_read_b128 v[116:119], v148
	ds_read_b128 v[128:131], v148 offset:1024
	ds_read_b128 v[140:143], v148 offset:2048
	ds_read_b128 v[148:151], v148 offset:3072
	v_lshl_add_u64 v[196:197], s[38:39], 0, v[222:223]
	s_add_i32 m0, s83, 0xc000
	ds_read_b128 v[160:163], v245
	ds_read_b128 v[168:171], v245 offset:1024
	ds_read_b128 v[172:175], v245 offset:2048
	ds_read_b128 v[176:179], v245 offset:3072
	ds_read_b128 v[180:183], v245 offset:4096
	ds_read_b128 v[184:187], v245 offset:5120
	ds_read_b128 v[188:191], v245 offset:6144
	ds_read_b128 v[192:195], v245 offset:7168
	global_load_lds_dwordx4 v[196:197], off
	v_lshl_add_u64 v[196:197], s[38:39], 0, v[220:221]
	s_add_i32 m0, s83, 0xe000
	s_nop 0
	global_load_lds_dwordx4 v[196:197], off
	s_waitcnt vmcnt(8)
	s_waitcnt lgkmcnt(0)
	s_barrier
	s_setprio 1
	s_waitcnt lgkmcnt(0)
	v_mfma_f32_16x16x32_bf16 v[164:167], v[92:95], v[160:163], v[164:167]
	v_mfma_f32_16x16x32_bf16 v[156:159], v[108:111], v[160:163], v[156:159]
	v_mfma_f32_16x16x32_bf16 v[136:139], v[92:95], v[172:175], v[136:139]
	v_mfma_f32_16x16x32_bf16 v[132:135], v[108:111], v[172:175], v[132:135]
	v_mfma_f32_16x16x32_bf16 v[104:107], v[92:95], v[180:183], v[104:107]
	v_mfma_f32_16x16x32_bf16 v[96:99], v[108:111], v[180:183], v[96:99]
	v_mfma_f32_16x16x32_bf16 v[80:83], v[92:95], v[188:191], v[80:83]
	v_mfma_f32_16x16x32_bf16 v[76:79], v[108:111], v[188:191], v[76:79]
	v_mfma_f32_16x16x32_bf16 v[164:167], v[100:103], v[168:171], v[164:167]
	v_mfma_f32_16x16x32_bf16 v[156:159], v[112:115], v[168:171], v[156:159]
	v_mfma_f32_16x16x32_bf16 v[136:139], v[100:103], v[176:179], v[136:139]
	v_mfma_f32_16x16x32_bf16 v[132:135], v[112:115], v[176:179], v[132:135]
	v_mfma_f32_16x16x32_bf16 v[104:107], v[100:103], v[184:187], v[104:107]
	v_mfma_f32_16x16x32_bf16 v[96:99], v[112:115], v[184:187], v[96:99]
	v_mfma_f32_16x16x32_bf16 v[80:83], v[100:103], v[192:195], v[80:83]
	v_mfma_f32_16x16x32_bf16 v[76:79], v[112:115], v[192:195], v[76:79]
	v_mfma_f32_16x16x32_bf16 v[152:155], v[116:119], v[160:163], v[152:155]
	v_mfma_f32_16x16x32_bf16 v[144:147], v[140:143], v[160:163], v[144:147]
	v_mfma_f32_16x16x32_bf16 v[124:127], v[116:119], v[172:175], v[124:127]
	v_mfma_f32_16x16x32_bf16 v[120:123], v[140:143], v[172:175], v[120:123]
	v_mfma_f32_16x16x32_bf16 v[88:91], v[116:119], v[180:183], v[88:91]
	v_mfma_f32_16x16x32_bf16 v[84:87], v[140:143], v[180:183], v[84:87]
	v_mfma_f32_16x16x32_bf16 v[72:75], v[116:119], v[188:191], v[72:75]
	v_mfma_f32_16x16x32_bf16 v[68:71], v[140:143], v[188:191], v[68:71]
	v_mfma_f32_16x16x32_bf16 v[152:155], v[128:131], v[168:171], v[152:155]
	v_mfma_f32_16x16x32_bf16 v[144:147], v[148:151], v[168:171], v[144:147]
	v_mfma_f32_16x16x32_bf16 v[124:127], v[128:131], v[176:179], v[124:127]
	v_mfma_f32_16x16x32_bf16 v[120:123], v[148:151], v[176:179], v[120:123]
	v_mfma_f32_16x16x32_bf16 v[88:91], v[128:131], v[184:187], v[88:91]
	v_mfma_f32_16x16x32_bf16 v[84:87], v[148:151], v[184:187], v[84:87]
	v_mfma_f32_16x16x32_bf16 v[72:75], v[128:131], v[192:195], v[72:75]
	v_mfma_f32_16x16x32_bf16 v[68:71], v[148:151], v[192:195], v[68:71]
	s_setprio 0
	s_barrier
	s_add_i32 s8, s8, s82
	v_lshl_add_u64 v[196:197], s[42:43], 0, v[2:3]
	s_mov_b32 m0, s8
	ds_read_b128 v[160:163], v245 offset:16384
	ds_read_b128 v[168:171], v245 offset:17408
	ds_read_b128 v[172:175], v245 offset:18432
	ds_read_b128 v[176:179], v245 offset:19456
	ds_read_b128 v[180:183], v245 offset:20480
	ds_read_b128 v[184:187], v245 offset:21504
	ds_read_b128 v[188:191], v245 offset:22528
	ds_read_b128 v[192:195], v245 offset:23552
	global_load_lds_dwordx4 v[196:197], off
	s_add_i32 m0, s8, 0x2000
	s_add_u32 s8, s42, 0x160000
	v_lshl_add_u64 v[198:199], s[42:43], 0, v[218:219]
	s_addc_u32 s9, s43, 0
	s_add_i32 s10, s10, s82
	global_load_lds_dwordx4 v[198:199], off
	v_lshl_add_u64 v[200:201], s[8:9], 0, v[2:3]
	s_mov_b32 m0, s10
	v_lshl_add_u64 v[202:203], s[44:45], 0, v[216:217]
	global_load_lds_dwordx4 v[200:201], off
	v_lshl_add_u64 v[200:201], s[8:9], 0, v[218:219]
	s_add_i32 m0, s10, 0x2000
	s_nop 0
	global_load_lds_dwordx4 v[200:201], off
	v_lshl_add_u64 v[200:201], s[44:45], 0, v[0:1]
	s_mov_b32 m0, s83
	s_nop 0
	global_load_lds_dwordx4 v[200:201], off
	s_mov_b32 m0, s84
	s_nop 0
	global_load_lds_dwordx4 v[202:203], off
	s_waitcnt vmcnt(8)
	s_waitcnt lgkmcnt(0)
	s_barrier
	s_setprio 1
	s_waitcnt lgkmcnt(0)
	v_mfma_f32_16x16x32_bf16 v[64:67], v[92:95], v[160:163], v[64:67]
	v_mfma_f32_16x16x32_bf16 v[60:63], v[108:111], v[160:163], v[60:63]
	v_mfma_f32_16x16x32_bf16 v[48:51], v[92:95], v[172:175], v[48:51]
	v_mfma_f32_16x16x32_bf16 v[44:47], v[108:111], v[172:175], v[44:47]
	v_mfma_f32_16x16x32_bf16 v[32:35], v[92:95], v[180:183], v[32:35]
	v_mfma_f32_16x16x32_bf16 v[28:31], v[108:111], v[180:183], v[28:31]
	v_mfma_f32_16x16x32_bf16 v[16:19], v[92:95], v[188:191], v[16:19]
	v_mfma_f32_16x16x32_bf16 v[12:15], v[108:111], v[188:191], v[12:15]
	v_mfma_f32_16x16x32_bf16 v[64:67], v[100:103], v[168:171], v[64:67]
	v_mfma_f32_16x16x32_bf16 v[60:63], v[112:115], v[168:171], v[60:63]
	v_mfma_f32_16x16x32_bf16 v[48:51], v[100:103], v[176:179], v[48:51]
	v_mfma_f32_16x16x32_bf16 v[44:47], v[112:115], v[176:179], v[44:47]
	v_mfma_f32_16x16x32_bf16 v[32:35], v[100:103], v[184:187], v[32:35]
	v_mfma_f32_16x16x32_bf16 v[28:31], v[112:115], v[184:187], v[28:31]
	v_mfma_f32_16x16x32_bf16 v[16:19], v[100:103], v[192:195], v[16:19]
	v_mfma_f32_16x16x32_bf16 v[12:15], v[112:115], v[192:195], v[12:15]
	v_mfma_f32_16x16x32_bf16 v[56:59], v[116:119], v[160:163], v[56:59]
	v_mfma_f32_16x16x32_bf16 v[52:55], v[140:143], v[160:163], v[52:55]
	v_mfma_f32_16x16x32_bf16 v[40:43], v[116:119], v[172:175], v[40:43]
	v_mfma_f32_16x16x32_bf16 v[36:39], v[140:143], v[172:175], v[36:39]
	v_mfma_f32_16x16x32_bf16 v[24:27], v[116:119], v[180:183], v[24:27]
	v_mfma_f32_16x16x32_bf16 v[20:23], v[140:143], v[180:183], v[20:23]
	v_mfma_f32_16x16x32_bf16 v[8:11], v[116:119], v[188:191], v[8:11]
	v_mfma_f32_16x16x32_bf16 v[4:7], v[140:143], v[188:191], v[4:7]
	v_mfma_f32_16x16x32_bf16 v[56:59], v[128:131], v[168:171], v[56:59]
	v_mfma_f32_16x16x32_bf16 v[52:55], v[148:151], v[168:171], v[52:55]
	v_mfma_f32_16x16x32_bf16 v[40:43], v[128:131], v[176:179], v[40:43]
	v_mfma_f32_16x16x32_bf16 v[36:39], v[148:151], v[176:179], v[36:39]
	v_mfma_f32_16x16x32_bf16 v[24:27], v[128:131], v[184:187], v[24:27]
	v_mfma_f32_16x16x32_bf16 v[20:23], v[148:151], v[184:187], v[20:23]
	v_mfma_f32_16x16x32_bf16 v[8:11], v[128:131], v[192:195], v[8:11]
	v_mfma_f32_16x16x32_bf16 v[4:7], v[148:151], v[192:195], v[4:7]
	s_setprio 0
	s_barrier
	s_add_i32 s10, 0, 0x18000
	s_add_i32 s11, 0, 0x1c000
	v_add_u32_e32 v112, s10, v242
	v_add_u32_e32 v148, s11, v242
	ds_read_b128 v[92:95], v112
	ds_read_b128 v[100:103], v112 offset:1024
	ds_read_b128 v[108:111], v112 offset:2048
	ds_read_b128 v[112:115], v112 offset:3072
	ds_read_b128 v[116:119], v148
	ds_read_b128 v[128:131], v148 offset:1024
	ds_read_b128 v[140:143], v148 offset:2048
	ds_read_b128 v[148:151], v148 offset:3072
	s_add_u32 s8, s44, 0x160000
	s_addc_u32 s9, s45, 0
	s_mov_b32 m0, s85
	v_lshl_add_u64 v[204:205], s[8:9], 0, v[0:1]
	ds_read_b128 v[160:163], v245 offset:32768
	ds_read_b128 v[168:171], v245 offset:33792
	ds_read_b128 v[172:175], v245 offset:34816
	ds_read_b128 v[176:179], v245 offset:35840
	ds_read_b128 v[180:183], v245 offset:36864
	ds_read_b128 v[184:187], v245 offset:37888
	ds_read_b128 v[188:191], v245 offset:38912
	ds_read_b128 v[192:195], v245 offset:39936
	global_load_lds_dwordx4 v[204:205], off
	v_lshl_add_u64 v[204:205], s[8:9], 0, v[216:217]
	s_mov_b32 m0, s87
	s_nop 0
	global_load_lds_dwordx4 v[204:205], off
	s_waitcnt vmcnt(8)
	s_waitcnt lgkmcnt(0)
	s_barrier
	s_setprio 1
	s_waitcnt lgkmcnt(0)
	v_mfma_f32_16x16x32_bf16 v[164:167], v[92:95], v[160:163], v[164:167]
	v_mfma_f32_16x16x32_bf16 v[156:159], v[108:111], v[160:163], v[156:159]
	v_mfma_f32_16x16x32_bf16 v[136:139], v[92:95], v[172:175], v[136:139]
	v_mfma_f32_16x16x32_bf16 v[132:135], v[108:111], v[172:175], v[132:135]
	v_mfma_f32_16x16x32_bf16 v[104:107], v[92:95], v[180:183], v[104:107]
	v_mfma_f32_16x16x32_bf16 v[96:99], v[108:111], v[180:183], v[96:99]
	v_mfma_f32_16x16x32_bf16 v[80:83], v[92:95], v[188:191], v[80:83]
	v_mfma_f32_16x16x32_bf16 v[76:79], v[108:111], v[188:191], v[76:79]
	v_mfma_f32_16x16x32_bf16 v[164:167], v[100:103], v[168:171], v[164:167]
	v_mfma_f32_16x16x32_bf16 v[156:159], v[112:115], v[168:171], v[156:159]
	v_mfma_f32_16x16x32_bf16 v[136:139], v[100:103], v[176:179], v[136:139]
	v_mfma_f32_16x16x32_bf16 v[132:135], v[112:115], v[176:179], v[132:135]
	v_mfma_f32_16x16x32_bf16 v[104:107], v[100:103], v[184:187], v[104:107]
	v_mfma_f32_16x16x32_bf16 v[96:99], v[112:115], v[184:187], v[96:99]
	v_mfma_f32_16x16x32_bf16 v[80:83], v[100:103], v[192:195], v[80:83]
	v_mfma_f32_16x16x32_bf16 v[76:79], v[112:115], v[192:195], v[76:79]
	v_mfma_f32_16x16x32_bf16 v[152:155], v[116:119], v[160:163], v[152:155]
	v_mfma_f32_16x16x32_bf16 v[144:147], v[140:143], v[160:163], v[144:147]
	v_mfma_f32_16x16x32_bf16 v[124:127], v[116:119], v[172:175], v[124:127]
	v_mfma_f32_16x16x32_bf16 v[120:123], v[140:143], v[172:175], v[120:123]
	v_mfma_f32_16x16x32_bf16 v[88:91], v[116:119], v[180:183], v[88:91]
	v_mfma_f32_16x16x32_bf16 v[84:87], v[140:143], v[180:183], v[84:87]
	v_mfma_f32_16x16x32_bf16 v[72:75], v[116:119], v[188:191], v[72:75]
	v_mfma_f32_16x16x32_bf16 v[68:71], v[140:143], v[188:191], v[68:71]
	v_mfma_f32_16x16x32_bf16 v[152:155], v[128:131], v[168:171], v[152:155]
	v_mfma_f32_16x16x32_bf16 v[144:147], v[148:151], v[168:171], v[144:147]
	v_mfma_f32_16x16x32_bf16 v[124:127], v[128:131], v[176:179], v[124:127]
	v_mfma_f32_16x16x32_bf16 v[120:123], v[148:151], v[176:179], v[120:123]
	v_mfma_f32_16x16x32_bf16 v[88:91], v[128:131], v[184:187], v[88:91]
	v_mfma_f32_16x16x32_bf16 v[84:87], v[148:151], v[184:187], v[84:87]
	v_mfma_f32_16x16x32_bf16 v[72:75], v[128:131], v[192:195], v[72:75]
	v_mfma_f32_16x16x32_bf16 v[68:71], v[148:151], v[192:195], v[68:71]
	s_setprio 0
	s_barrier
	s_add_i32 s8, s10, s82
	v_lshl_add_u64 v[196:197], v[196:197], 0, s[68:69]
	s_mov_b32 m0, s8
	ds_read_b128 v[160:163], v245 offset:49152
	ds_read_b128 v[168:171], v245 offset:50176
	ds_read_b128 v[172:175], v245 offset:51200
	ds_read_b128 v[176:179], v245 offset:52224
	ds_read_b128 v[180:183], v245 offset:53248
	ds_read_b128 v[184:187], v245 offset:54272
	ds_read_b128 v[188:191], v245 offset:55296
	ds_read_b128 v[192:195], v245 offset:56320
	global_load_lds_dwordx4 v[196:197], off
	s_add_i32 m0, s8, 0x2000
	s_add_u32 s8, s42, 0x160080
	v_lshl_add_u64 v[196:197], v[198:199], 0, s[68:69]
	s_addc_u32 s9, s43, 0
	s_add_i32 s10, s11, s82
	global_load_lds_dwordx4 v[196:197], off
	v_lshl_add_u64 v[196:197], s[8:9], 0, v[2:3]
	s_mov_b32 m0, s10
	s_nop 0
	global_load_lds_dwordx4 v[196:197], off
	v_lshl_add_u64 v[196:197], s[8:9], 0, v[218:219]
	s_add_i32 m0, s10, 0x2000
	s_nop 0
	global_load_lds_dwordx4 v[196:197], off
	v_lshl_add_u64 v[196:197], v[200:201], 0, s[68:69]
	s_mov_b32 m0, s72
	s_nop 0
	global_load_lds_dwordx4 v[196:197], off
	v_lshl_add_u64 v[196:197], v[202:203], 0, s[68:69]
	s_mov_b32 m0, s88
	s_nop 0
	global_load_lds_dwordx4 v[196:197], off
	s_waitcnt vmcnt(8)
	s_waitcnt lgkmcnt(0)
	s_barrier
	s_setprio 1
	s_waitcnt lgkmcnt(0)
	v_mfma_f32_16x16x32_bf16 v[64:67], v[92:95], v[160:163], v[64:67]
	v_mfma_f32_16x16x32_bf16 v[60:63], v[108:111], v[160:163], v[60:63]
	v_mfma_f32_16x16x32_bf16 v[48:51], v[92:95], v[172:175], v[48:51]
	v_mfma_f32_16x16x32_bf16 v[44:47], v[108:111], v[172:175], v[44:47]
	v_mfma_f32_16x16x32_bf16 v[32:35], v[92:95], v[180:183], v[32:35]
	v_mfma_f32_16x16x32_bf16 v[28:31], v[108:111], v[180:183], v[28:31]
	v_mfma_f32_16x16x32_bf16 v[16:19], v[92:95], v[188:191], v[16:19]
	v_mfma_f32_16x16x32_bf16 v[12:15], v[108:111], v[188:191], v[12:15]
	v_mfma_f32_16x16x32_bf16 v[64:67], v[100:103], v[168:171], v[64:67]
	v_mfma_f32_16x16x32_bf16 v[60:63], v[112:115], v[168:171], v[60:63]
	v_mfma_f32_16x16x32_bf16 v[48:51], v[100:103], v[176:179], v[48:51]
	v_mfma_f32_16x16x32_bf16 v[44:47], v[112:115], v[176:179], v[44:47]
	v_mfma_f32_16x16x32_bf16 v[32:35], v[100:103], v[184:187], v[32:35]
	v_mfma_f32_16x16x32_bf16 v[28:31], v[112:115], v[184:187], v[28:31]
	v_mfma_f32_16x16x32_bf16 v[16:19], v[100:103], v[192:195], v[16:19]
	v_mfma_f32_16x16x32_bf16 v[12:15], v[112:115], v[192:195], v[12:15]
	v_mfma_f32_16x16x32_bf16 v[56:59], v[116:119], v[160:163], v[56:59]
	v_mfma_f32_16x16x32_bf16 v[52:55], v[140:143], v[160:163], v[52:55]
	v_mfma_f32_16x16x32_bf16 v[40:43], v[116:119], v[172:175], v[40:43]
	v_mfma_f32_16x16x32_bf16 v[36:39], v[140:143], v[172:175], v[36:39]
	v_mfma_f32_16x16x32_bf16 v[24:27], v[116:119], v[180:183], v[24:27]
	v_mfma_f32_16x16x32_bf16 v[20:23], v[140:143], v[180:183], v[20:23]
	v_mfma_f32_16x16x32_bf16 v[8:11], v[116:119], v[188:191], v[8:11]
	v_mfma_f32_16x16x32_bf16 v[4:7], v[140:143], v[188:191], v[4:7]
	v_mfma_f32_16x16x32_bf16 v[56:59], v[128:131], v[168:171], v[56:59]
	v_mfma_f32_16x16x32_bf16 v[52:55], v[148:151], v[168:171], v[52:55]
	v_mfma_f32_16x16x32_bf16 v[40:43], v[128:131], v[176:179], v[40:43]
	v_mfma_f32_16x16x32_bf16 v[36:39], v[148:151], v[176:179], v[36:39]
	v_mfma_f32_16x16x32_bf16 v[24:27], v[128:131], v[184:187], v[24:27]
	v_mfma_f32_16x16x32_bf16 v[20:23], v[148:151], v[184:187], v[20:23]
	v_mfma_f32_16x16x32_bf16 v[8:11], v[128:131], v[192:195], v[8:11]
	v_mfma_f32_16x16x32_bf16 v[4:7], v[148:151], v[192:195], v[4:7]
	s_setprio 0
	s_barrier
	s_add_i32 s7, s7, 2
	s_add_u32 s5, s5, 0x100
	s_addc_u32 s6, s6, 0
	s_cmpk_gt_u32 s7, 0x55
	s_mov_b64 s[38:39], s[40:41]
	s_cbranch_scc0 .LBB0_1134
	s_and_b64 vcc, exec, s[52:53]
	s_cbranch_vccz .LBB0_1137
	s_barrier
